# software-pipelined LDS fragment prefetch in 5 big GEMM K-loops (A ping-pong regs, early barrier) + diff-attn K/V LDS double-buffer removing one barrier per tile
# speedup vs baseline: 1.0268x; 1.0268x over previous
; #define MFMA16(a, b, c) __builtin_amdgcn_mfma_f32_16x16x32_bf16((a), (b), (c), 0, 0, 0)
; DI void vm_wait0() { asm volatile("s_waitcnt vmcnt(0)" ::: "memory"); }
;   DI unsigned koff(int k) const { return (unsigned)((k >> 6) * EIN + (k & 63)); }
; DI void dma16(const void* g, unsigned char* l) { __builtin_amdgcn_global_load_lds((const unsigned*)g, (lds_u32_t*)(unsigned)(size_t)l, 16, 0, 0); }
; template <class AF, class EF>
; DI void gemm_run(unsigned char* lds, int wv, const AF& af, const bf16_t* __restrict__ Bt, int ldb, int M, int N, int K, const EF& ef, int blk_off) {
;     ...
;     for (int kt = 0; kt < nk; ++kt) {
;       unsigned char* cur = sBase + (kt & 1) * GST;
;       if (kt + 1 < nk) {
;         unsigned char* nxt = sBase + ((kt + 1) & 1) * GST;
;         const int k0 = (kt + 1) << 6;
; #pragma unroll
;         for (int i = 0; i < 4; ++i) {
;           dma16(Ab + aoff[i] + af.koff(k0 + cch), nxt + 32768 + (i * 512 + tid) * 16);
;           dma16(Bt + boff[i] + (unsigned)k0, nxt + (i * 512 + tid) * 16);
;         }
;       }
; #pragma unroll
;       for (int ks = 0; ks < 2; ++ks) {
;         bf16x8 wf[4], xf[8];
; #pragma unroll
;         for (int i = 0; i < 4; ++i) wf[i] = *(const bf16x8*)(cur + (wn * 64 + i * 16 + l15) * 128 + (((ks * 4 + q4) ^ swz) * 16));
; #pragma unroll
;         for (int j = 0; j < 8; ++j) xf[j] = *(const bf16x8*)(cur + 32768 + (wm * 128 + j * 16 + l15) * 128 + (((ks * 4 + q4) ^ swz) * 16));
; #pragma unroll
;         for (int i = 0; i < 4; ++i)
; #pragma unroll
;           for (int j = 0; j < 8; ++j) acc[i][j] = MFMA16(wf[i], xf[j], acc[i][j]);
;       }
;       vm_wait0();
;       __syncthreads();
;     }
.LBB0_121:
	s_add_i32 s100, s14, 0xffff0000
	s_and_b32 s100, s100, 0x10000
	v_add_u32_e32 v0, s100, v175
	v_add3_u32 v212, v0, v176, v177
	v_add3_u32 v0, v0, v178, v177
	ds_read_b128 v[130:133], v212 offset:8192
	ds_read_b128 v[180:183], v0 offset:40960
	ds_read_b128 v[184:187], v0 offset:43008
	ds_read_b128 v[188:191], v0 offset:45056
	ds_read_b128 v[192:195], v0 offset:47104
	ds_read_b128 v[196:199], v0 offset:49152
	ds_read_b128 v[200:203], v0 offset:51200
	ds_read_b128 v[204:207], v0 offset:53248
	ds_read_b128 v[208:211], v0 offset:55296
	s_cmpk_eq_i32 s4, 0x780
	s_cbranch_scc1 .Lmyg120_loop
	s_and_b32 s15, s14, 0x10000
	s_add_i32 s15, s15, 0
	s_add_i32 s16, s15, 0x2000
	s_add_i32 s15, s15, 0xa000
	v_add_u32_e32 v224, s15, v136
	v_lshl_add_u64 v[222:223], v[160:161], 0, s[4:5]
	v_readfirstlane_b32 s17, v224
	v_add_u32_e32 v224, s16, v136
	s_mov_b32 m0, s17
	v_readfirstlane_b32 s17, v224
	v_add_u32_e32 v224, s15, v138
	global_load_lds_dwordx4 v[222:223], off
	v_lshl_add_u64 v[222:223], v[152:153], 0, s[4:5]
	s_mov_b32 m0, s17
	v_readfirstlane_b32 s17, v224
	v_add_u32_e32 v224, s16, v138
	global_load_lds_dwordx4 v[222:223], off
	v_lshl_add_u64 v[222:223], v[158:159], 0, s[4:5]
	s_mov_b32 m0, s17
	v_readfirstlane_b32 s17, v224
	v_add_u32_e32 v224, s15, v140
	global_load_lds_dwordx4 v[222:223], off
	v_lshl_add_u64 v[222:223], v[150:151], 0, s[4:5]
	s_mov_b32 m0, s17
	v_readfirstlane_b32 s17, v224
	v_add_u32_e32 v224, s16, v140
	global_load_lds_dwordx4 v[222:223], off
	v_lshl_add_u64 v[222:223], v[156:157], 0, s[4:5]
	s_mov_b32 m0, s17
	v_readfirstlane_b32 s17, v224
	v_add_u32_e32 v224, s15, v142
	global_load_lds_dwordx4 v[222:223], off
	v_lshl_add_u64 v[222:223], v[148:149], 0, s[4:5]
	s_mov_b32 m0, s17
	v_readfirstlane_b32 s15, v224
	v_add_u32_e32 v224, s16, v142
	global_load_lds_dwordx4 v[222:223], off
	v_lshl_add_u64 v[222:223], v[154:155], 0, s[4:5]
	s_mov_b32 m0, s15
	v_readfirstlane_b32 s15, v224
	global_load_lds_dwordx4 v[222:223], off
	v_lshl_add_u64 v[222:223], v[146:147], 0, s[4:5]
	s_mov_b32 m0, s15
	s_nop 0
	global_load_lds_dwordx4 v[222:223], off
.Lmyg120_loop:
	s_waitcnt lgkmcnt(7)
	v_mfma_f32_16x16x32_bf16 v[126:129], v[130:133], v[180:183], v[126:129]
	ds_read_b128 v[226:229], v212 offset:10240
	s_waitcnt lgkmcnt(7)
	v_mfma_f32_16x16x32_bf16 v[118:121], v[130:133], v[184:187], v[118:121]
	s_waitcnt lgkmcnt(6)
	v_mfma_f32_16x16x32_bf16 v[110:113], v[130:133], v[188:191], v[110:113]
	s_waitcnt lgkmcnt(5)
	v_mfma_f32_16x16x32_bf16 v[102:105], v[130:133], v[192:195], v[102:105]
	s_waitcnt lgkmcnt(4)
	v_mfma_f32_16x16x32_bf16 v[94:97], v[130:133], v[196:199], v[94:97]
	s_waitcnt lgkmcnt(3)
	v_mfma_f32_16x16x32_bf16 v[86:89], v[130:133], v[200:203], v[86:89]
	s_waitcnt lgkmcnt(2)
	v_mfma_f32_16x16x32_bf16 v[78:81], v[130:133], v[204:207], v[78:81]
	s_waitcnt lgkmcnt(1)
	v_mfma_f32_16x16x32_bf16 v[70:73], v[130:133], v[208:211], v[70:73]
	s_waitcnt lgkmcnt(0)
	v_mfma_f32_16x16x32_bf16 v[122:125], v[226:229], v[180:183], v[122:125]
	ds_read_b128 v[130:133], v212 offset:12288
	v_mfma_f32_16x16x32_bf16 v[114:117], v[226:229], v[184:187], v[114:117]
	v_mfma_f32_16x16x32_bf16 v[106:109], v[226:229], v[188:191], v[106:109]
	v_mfma_f32_16x16x32_bf16 v[98:101], v[226:229], v[192:195], v[98:101]
	v_mfma_f32_16x16x32_bf16 v[90:93], v[226:229], v[196:199], v[90:93]
	v_mfma_f32_16x16x32_bf16 v[82:85], v[226:229], v[200:203], v[82:85]
	v_mfma_f32_16x16x32_bf16 v[74:77], v[226:229], v[204:207], v[74:77]
	v_mfma_f32_16x16x32_bf16 v[66:69], v[226:229], v[208:211], v[66:69]
	s_waitcnt lgkmcnt(0)
	v_mfma_f32_16x16x32_bf16 v[58:61], v[130:133], v[180:183], v[58:61]
	ds_read_b128 v[226:229], v212 offset:14336
	v_mfma_f32_16x16x32_bf16 v[50:53], v[130:133], v[184:187], v[50:53]
	v_add_u32_e32 v0, s100, v179
	v_mfma_f32_16x16x32_bf16 v[42:45], v[130:133], v[188:191], v[42:45]
	v_add3_u32 v212, v0, v176, v177
	v_mfma_f32_16x16x32_bf16 v[34:37], v[130:133], v[192:195], v[34:37]
	v_add3_u32 v0, v0, v178, v177
	v_mfma_f32_16x16x32_bf16 v[26:29], v[130:133], v[196:199], v[26:29]
	v_mfma_f32_16x16x32_bf16 v[18:21], v[130:133], v[200:203], v[18:21]
	v_mfma_f32_16x16x32_bf16 v[6:9], v[130:133], v[204:207], v[6:9]
	v_mfma_f32_16x16x32_bf16 v[2:5], v[130:133], v[208:211], v[2:5]
	s_waitcnt lgkmcnt(0)
	v_mfma_f32_16x16x32_bf16 v[62:65], v[226:229], v[180:183], v[62:65]
	ds_read_b128 v[130:133], v212 offset:8192
	ds_read_b128 v[180:183], v0 offset:40960
	v_mfma_f32_16x16x32_bf16 v[54:57], v[226:229], v[184:187], v[54:57]
	ds_read_b128 v[184:187], v0 offset:43008
	v_mfma_f32_16x16x32_bf16 v[46:49], v[226:229], v[188:191], v[46:49]
	ds_read_b128 v[188:191], v0 offset:45056
	v_mfma_f32_16x16x32_bf16 v[38:41], v[226:229], v[192:195], v[38:41]
	ds_read_b128 v[192:195], v0 offset:47104
	v_mfma_f32_16x16x32_bf16 v[30:33], v[226:229], v[196:199], v[30:33]
	ds_read_b128 v[196:199], v0 offset:49152
	v_mfma_f32_16x16x32_bf16 v[22:25], v[226:229], v[200:203], v[22:25]
	ds_read_b128 v[200:203], v0 offset:51200
	v_mfma_f32_16x16x32_bf16 v[14:17], v[226:229], v[204:207], v[14:17]
	ds_read_b128 v[204:207], v0 offset:53248
	v_mfma_f32_16x16x32_bf16 v[10:13], v[226:229], v[208:211], v[10:13]
	ds_read_b128 v[208:211], v0 offset:55296
	s_waitcnt lgkmcnt(7)
	v_mfma_f32_16x16x32_bf16 v[126:129], v[130:133], v[180:183], v[126:129]
	ds_read_b128 v[226:229], v212 offset:10240
	s_waitcnt lgkmcnt(7)
; #define MFMA16(a, b, c) __builtin_amdgcn_mfma_f32_16x16x32_bf16((a), (b), (c), 0, 0, 0)
; DI void vm_wait0() { asm volatile("s_waitcnt vmcnt(0)" ::: "memory"); }
;   DI unsigned koff(int k) const { return (unsigned)((k >> 6) * EIN + (k & 63)); }
; DI void dma16(const void* g, unsigned char* l) { __builtin_amdgcn_global_load_lds((const unsigned*)g, (lds_u32_t*)(unsigned)(size_t)l, 16, 0, 0); }
; template <class AF, class EF>
; DI void gemm_run(unsigned char* lds, int wv, const AF& af, const bf16_t* __restrict__ Bt, int ldb, int M, int N, int K, const EF& ef, int blk_off) {
;     ...
;     for (int kt = 0; kt < nk; ++kt) {
;       unsigned char* cur = sBase + (kt & 1) * GST;
;       if (kt + 1 < nk) {
;         unsigned char* nxt = sBase + ((kt + 1) & 1) * GST;
;         const int k0 = (kt + 1) << 6;
; #pragma unroll
;         for (int i = 0; i < 4; ++i) {
;           dma16(Ab + aoff[i] + af.koff(k0 + cch), nxt + 32768 + (i * 512 + tid) * 16);
;           dma16(Bt + boff[i] + (unsigned)k0, nxt + (i * 512 + tid) * 16);
;         }
;       }
; #pragma unroll
;       for (int ks = 0; ks < 2; ++ks) {
;         bf16x8 wf[4], xf[8];
; #pragma unroll
;         for (int i = 0; i < 4; ++i) wf[i] = *(const bf16x8*)(cur + (wn * 64 + i * 16 + l15) * 128 + (((ks * 4 + q4) ^ swz) * 16));
; #pragma unroll
;         for (int j = 0; j < 8; ++j) xf[j] = *(const bf16x8*)(cur + 32768 + (wm * 128 + j * 16 + l15) * 128 + (((ks * 4 + q4) ^ swz) * 16));
; #pragma unroll
;         for (int i = 0; i < 4; ++i)
; #pragma unroll
;           for (int j = 0; j < 8; ++j) acc[i][j] = MFMA16(wf[i], xf[j], acc[i][j]);
;       }
;       vm_wait0();
;       __syncthreads();
;     }
	v_mfma_f32_16x16x32_bf16 v[118:121], v[130:133], v[184:187], v[118:121]
	s_waitcnt lgkmcnt(6)
	v_mfma_f32_16x16x32_bf16 v[110:113], v[130:133], v[188:191], v[110:113]
	s_waitcnt lgkmcnt(5)
	v_mfma_f32_16x16x32_bf16 v[102:105], v[130:133], v[192:195], v[102:105]
	s_waitcnt lgkmcnt(4)
	v_mfma_f32_16x16x32_bf16 v[94:97], v[130:133], v[196:199], v[94:97]
	s_waitcnt lgkmcnt(3)
	v_mfma_f32_16x16x32_bf16 v[86:89], v[130:133], v[200:203], v[86:89]
	s_waitcnt lgkmcnt(2)
	v_mfma_f32_16x16x32_bf16 v[78:81], v[130:133], v[204:207], v[78:81]
	s_waitcnt lgkmcnt(1)
	v_mfma_f32_16x16x32_bf16 v[70:73], v[130:133], v[208:211], v[70:73]
	s_waitcnt lgkmcnt(0)
	v_mfma_f32_16x16x32_bf16 v[122:125], v[226:229], v[180:183], v[122:125]
	ds_read_b128 v[130:133], v212 offset:12288
	v_mfma_f32_16x16x32_bf16 v[114:117], v[226:229], v[184:187], v[114:117]
	v_mfma_f32_16x16x32_bf16 v[106:109], v[226:229], v[188:191], v[106:109]
	v_mfma_f32_16x16x32_bf16 v[98:101], v[226:229], v[192:195], v[98:101]
	v_mfma_f32_16x16x32_bf16 v[90:93], v[226:229], v[196:199], v[90:93]
	v_mfma_f32_16x16x32_bf16 v[82:85], v[226:229], v[200:203], v[82:85]
	v_mfma_f32_16x16x32_bf16 v[74:77], v[226:229], v[204:207], v[74:77]
	v_mfma_f32_16x16x32_bf16 v[66:69], v[226:229], v[208:211], v[66:69]
	s_waitcnt lgkmcnt(0)
	v_mfma_f32_16x16x32_bf16 v[58:61], v[130:133], v[180:183], v[58:61]
	ds_read_b128 v[226:229], v212 offset:14336
	v_mfma_f32_16x16x32_bf16 v[50:53], v[130:133], v[184:187], v[50:53]
	v_mfma_f32_16x16x32_bf16 v[42:45], v[130:133], v[188:191], v[42:45]
	v_mfma_f32_16x16x32_bf16 v[34:37], v[130:133], v[192:195], v[34:37]
	v_mfma_f32_16x16x32_bf16 v[26:29], v[130:133], v[196:199], v[26:29]
	v_mfma_f32_16x16x32_bf16 v[18:21], v[130:133], v[200:203], v[18:21]
	v_mfma_f32_16x16x32_bf16 v[6:9], v[130:133], v[204:207], v[6:9]
	v_mfma_f32_16x16x32_bf16 v[2:5], v[130:133], v[208:211], v[2:5]
	s_waitcnt vmcnt(0) lgkmcnt(0)
	s_barrier
	s_add_u32 s4, s4, 0x80
	s_addc_u32 s5, s5, 0
	s_add_i32 s14, s14, 0x10000
	s_cmpk_eq_i32 s4, 0x800
	s_cbranch_scc1 .Lmyg120_tail
	s_add_i32 s100, s14, 0xffff0000
	s_and_b32 s100, s100, 0x10000
	v_add_u32_e32 v0, s100, v175
	v_add3_u32 v212, v0, v176, v177
	v_add3_u32 v0, v0, v178, v177
	s_cmpk_eq_i32 s4, 0x780
	v_mfma_f32_16x16x32_bf16 v[62:65], v[226:229], v[180:183], v[62:65]
	ds_read_b128 v[130:133], v212 offset:8192
	ds_read_b128 v[180:183], v0 offset:40960
	v_mfma_f32_16x16x32_bf16 v[54:57], v[226:229], v[184:187], v[54:57]
	ds_read_b128 v[184:187], v0 offset:43008
	v_mfma_f32_16x16x32_bf16 v[46:49], v[226:229], v[188:191], v[46:49]
	ds_read_b128 v[188:191], v0 offset:45056
	v_mfma_f32_16x16x32_bf16 v[38:41], v[226:229], v[192:195], v[38:41]
	ds_read_b128 v[192:195], v0 offset:47104
	v_mfma_f32_16x16x32_bf16 v[30:33], v[226:229], v[196:199], v[30:33]
	ds_read_b128 v[196:199], v0 offset:49152
	v_mfma_f32_16x16x32_bf16 v[22:25], v[226:229], v[200:203], v[22:25]
	ds_read_b128 v[200:203], v0 offset:51200
	v_mfma_f32_16x16x32_bf16 v[14:17], v[226:229], v[204:207], v[14:17]
	ds_read_b128 v[204:207], v0 offset:53248
	v_mfma_f32_16x16x32_bf16 v[10:13], v[226:229], v[208:211], v[10:13]
	ds_read_b128 v[208:211], v0 offset:55296
	s_cbranch_scc1 .Lmyg120_loop
	s_and_b32 s15, s14, 0x10000
	s_add_i32 s15, s15, 0
	s_add_i32 s16, s15, 0x2000
	s_add_i32 s15, s15, 0xa000
	v_add_u32_e32 v224, s15, v136
	v_lshl_add_u64 v[222:223], v[160:161], 0, s[4:5]
	v_readfirstlane_b32 s17, v224
	v_add_u32_e32 v224, s16, v136
	s_mov_b32 m0, s17
	v_readfirstlane_b32 s17, v224
	v_add_u32_e32 v224, s15, v138
	global_load_lds_dwordx4 v[222:223], off
	v_lshl_add_u64 v[222:223], v[152:153], 0, s[4:5]
	s_mov_b32 m0, s17
	v_readfirstlane_b32 s17, v224
	v_add_u32_e32 v224, s16, v138
	global_load_lds_dwordx4 v[222:223], off
	v_lshl_add_u64 v[222:223], v[158:159], 0, s[4:5]
	s_mov_b32 m0, s17
	v_readfirstlane_b32 s17, v224
	v_add_u32_e32 v224, s15, v140
	global_load_lds_dwordx4 v[222:223], off
	v_lshl_add_u64 v[222:223], v[150:151], 0, s[4:5]
	s_mov_b32 m0, s17
	v_readfirstlane_b32 s17, v224
	v_add_u32_e32 v224, s16, v140
	global_load_lds_dwordx4 v[222:223], off
	v_lshl_add_u64 v[222:223], v[156:157], 0, s[4:5]
	s_mov_b32 m0, s17
	v_readfirstlane_b32 s17, v224
	v_add_u32_e32 v224, s15, v142
	global_load_lds_dwordx4 v[222:223], off
	v_lshl_add_u64 v[222:223], v[148:149], 0, s[4:5]
	s_mov_b32 m0, s17
	v_readfirstlane_b32 s15, v224
	v_add_u32_e32 v224, s16, v142
	global_load_lds_dwordx4 v[222:223], off
	v_lshl_add_u64 v[222:223], v[154:155], 0, s[4:5]
	s_mov_b32 m0, s15
	v_readfirstlane_b32 s15, v224
	global_load_lds_dwordx4 v[222:223], off
	v_lshl_add_u64 v[222:223], v[146:147], 0, s[4:5]
	s_mov_b32 m0, s15
	s_nop 0
	global_load_lds_dwordx4 v[222:223], off
	s_branch .Lmyg120_loop
.Lmyg120_tail:
	v_mfma_f32_16x16x32_bf16 v[62:65], v[226:229], v[180:183], v[62:65]
	v_mfma_f32_16x16x32_bf16 v[54:57], v[226:229], v[184:187], v[54:57]
	v_mfma_f32_16x16x32_bf16 v[46:49], v[226:229], v[188:191], v[46:49]
	v_mfma_f32_16x16x32_bf16 v[38:41], v[226:229], v[192:195], v[38:41]
	v_mfma_f32_16x16x32_bf16 v[30:33], v[226:229], v[196:199], v[30:33]
	v_mfma_f32_16x16x32_bf16 v[22:25], v[226:229], v[200:203], v[22:25]
	v_mfma_f32_16x16x32_bf16 v[14:17], v[226:229], v[204:207], v[14:17]
	v_mfma_f32_16x16x32_bf16 v[10:13], v[226:229], v[208:211], v[10:13]
	s_branch .LBB0_123

; DI void vm_wait0() { asm volatile("s_waitcnt vmcnt(0)" ::: "memory"); }
; DI void diff_attn_phase(unsigned char* lds, KParamPtr P, int wv, int l) {
;     ...
;       const int col = h * 2 + pass;
;       bf16x8 qf[4];
;       const bf16_t* qp = qk + (size_t)(b * SEQ + t) * 2048 + h * 128 + pass * 64 + hh * 8;
; #pragma unroll
;       for (int ks = 0; ks < 4; ++ks) qf[ks] = ldg8(qp + ks * 16);
;       f32x16 O[4];
; #pragma unroll
;       for (int e = 0; e < 4; ++e) O[e] = zero16();
;       float m_run = NEGB, l_run = 0.f;
;       const float bfar = tab[col * 128 + 127];
;       const unsigned kgo = (unsigned)((b * SEQ + (tid >> 3)) * 2048 + 1024 + h * 128 + pass * 64 + (tid & 7) * 8);
;       const unsigned vgo = (unsigned)(((b * 8 + h) * 128 + (tid >> 3)) * SEQ + (tid & 7) * 8);
;       u32x4 rk = *(const u32x4*)(qk + kgo), rv0 = *(const u32x4*)(vT + vgo), rv1 = *(const u32x4*)(vT + vgo + 64 * SEQ);
;       __syncthreads();
;       *(u32x4*)(sK + (tid >> 3) * LROW + (tid & 7) * 8) = rk;
;       *(u32x4*)(sV + (tid >> 3) * LROW + (tid & 7) * 8) = rv0;
;       *(u32x4*)(sV + ((tid >> 3) + 64) * LROW + (tid & 7) * 8) = rv1;
;       __syncthreads();
;     ...
;         __syncthreads();
;         vm_wait0();
;         if (kt + 1 < nkt) {
;           *(u32x4*)(sK + (tid >> 3) * LROW + (tid & 7) * 8) = rk;
;           *(u32x4*)(sV + (tid >> 3) * LROW + (tid & 7) * 8) = rv0;
;           *(u32x4*)(sV + ((tid >> 3) + 64) * LROW + (tid & 7) * 8) = rv1;
;         }
;         __syncthreads();
.LBB0_215:
	s_xor_b64 s[16:17], s[4:5], -1
	s_lshl_b32 s5, s18, 9
	s_lshl_b32 s88, s18, 7
	s_add_i32 s36, s31, s5
	s_lshl_b32 s4, s18, 6
	v_lshl_add_u64 v[2:3], v[186:187], 0, s[88:89]
	v_mov_b32_e32 v0, s36
	flat_load_dwordx4 v[112:115], v[2:3]
	flat_load_dwordx4 v[116:119], v[2:3] offset:32
	flat_load_dwordx4 v[120:123], v[2:3] offset:64
	flat_load_dwordx4 v[124:127], v[2:3] offset:96
	ds_read_b32 v223, v0 offset:508
	v_or_b32_e32 v0, s4, v181
	v_lshl_add_u64 v[2:3], v[0:1], 1, s[10:11]
	flat_load_dwordx4 v[128:131], v[2:3]
	flat_load_dwordx4 v[132:135], v[188:189]
	flat_load_dwordx4 v[136:139], v[190:191]
	v_add_u32_e32 v0, s4, v222
	v_mov_b32_e32 v14, v1
	v_mov_b32_e32 v15, v1
	v_lshl_add_u64 v[196:197], v[0:1], 1, s[12:13]
	v_mov_b32_e32 v0, v1
	v_mov_b32_e32 v2, v1
	v_mov_b32_e32 v3, v1
	v_mov_b32_e32 v4, v1
	v_mov_b32_e32 v5, v1
	v_mov_b32_e32 v6, v1
	v_mov_b32_e32 v7, v1
	v_mov_b32_e32 v8, v1
	v_mov_b32_e32 v9, v1
	v_mov_b32_e32 v10, v1
	v_mov_b32_e32 v11, v1
	v_mov_b32_e32 v12, v1
	v_mov_b32_e32 v13, v1
	v_mov_b64_e32 v[30:31], v[14:15]
	v_mov_b64_e32 v[46:47], v[14:15]
	v_mov_b64_e32 v[62:63], v[14:15]
	v_mov_b64_e32 v[78:79], v[14:15]
	s_mov_b32 s37, 1
	v_mov_b32_e32 v224, 0
	v_mov_b32_e32 v225, 0xf149f2ca
	v_mov_b64_e32 v[198:199], v[194:195]
	s_mov_b32 s38, 0
	s_mov_b32 s40, 0
	v_mov_b64_e32 v[28:29], v[12:13]
	v_mov_b64_e32 v[26:27], v[10:11]
	v_mov_b64_e32 v[24:25], v[8:9]
	v_mov_b64_e32 v[22:23], v[6:7]
	v_mov_b64_e32 v[20:21], v[4:5]
	v_mov_b64_e32 v[18:19], v[2:3]
	v_mov_b64_e32 v[16:17], v[0:1]
	v_mov_b64_e32 v[44:45], v[12:13]
	v_mov_b64_e32 v[42:43], v[10:11]
	v_mov_b64_e32 v[40:41], v[8:9]
	v_mov_b64_e32 v[38:39], v[6:7]
	v_mov_b64_e32 v[36:37], v[4:5]
	v_mov_b64_e32 v[34:35], v[2:3]
	v_mov_b64_e32 v[32:33], v[0:1]
	v_mov_b64_e32 v[60:61], v[12:13]
	v_mov_b64_e32 v[58:59], v[10:11]
	v_mov_b64_e32 v[56:57], v[8:9]
	v_mov_b64_e32 v[54:55], v[6:7]
	v_mov_b64_e32 v[52:53], v[4:5]
	v_mov_b64_e32 v[50:51], v[2:3]
	v_mov_b64_e32 v[48:49], v[0:1]
	v_mov_b64_e32 v[76:77], v[12:13]
	v_mov_b64_e32 v[74:75], v[10:11]
	v_mov_b64_e32 v[72:73], v[8:9]
	v_mov_b64_e32 v[70:71], v[6:7]
	v_mov_b64_e32 v[68:69], v[4:5]
	v_mov_b64_e32 v[66:67], v[2:3]
	v_mov_b64_e32 v[64:65], v[0:1]
	s_waitcnt lgkmcnt(0)
	s_barrier
	s_waitcnt vmcnt(0)
	ds_write_b128 v207, v[128:131] offset:8192
	ds_write_b128 v207, v[132:135] offset:17408
	ds_write_b128 v207, v[136:139] offset:26624
	s_waitcnt lgkmcnt(0)
	s_barrier
	v_xor_b32_e32 v207, 0x18000, v207
	s_branch .LBB0_217
.LBB0_216:
	v_xor_b32_e32 v207, 0x18000, v207
	v_xor_b32_e32 v210, 0x18000, v210
	v_xor_b32_e32 v211, 0x18000, v211
	s_sub_i32 s38, s38, 64
	s_mov_b64 s[4:5], 0x40000
	s_add_i32 s40, s40, 64
	v_lshl_add_u64 v[196:197], v[196:197], 0, s[4:5]
	s_add_i32 s4, s29, s38
	s_add_i32 s37, s37, 1
	s_cmpk_eq_i32 s4, 0xff00
	v_lshl_add_u64 v[198:199], v[198:199], 0, s[92:93]
	s_waitcnt lgkmcnt(0)
	s_barrier
	s_cbranch_scc1 .LBB0_245

; DI float red_sum32(float x) { auto r = __builtin_amdgcn_permlane32_swap(__float_as_uint(x), __float_as_uint(x), false, false); return __uint_as_float(r[0]) + __uint_as_float(r[1]); }
; DI void vm_wait0() { asm volatile("s_waitcnt vmcnt(0)" ::: "memory"); }
; DI void diff_attn_phase(unsigned char* lds, KParamPtr P, int wv, int l) {
;     ...
;         __syncthreads();
;         vm_wait0();
;         if (kt + 1 < nkt) {
;           *(u32x4*)(sK + (tid >> 3) * LROW + (tid & 7) * 8) = rk;
;           *(u32x4*)(sV + (tid >> 3) * LROW + (tid & 7) * 8) = rv0;
;           *(u32x4*)(sV + ((tid >> 3) + 64) * LROW + (tid & 7) * 8) = rv1;
;         }
;         __syncthreads();
;       }
;       const float lt = red_sum32(l_run);
;       const float inv = 1.f / lt;
.LBB0_243:
	s_or_b64 exec, exec, s[20:21]
	s_waitcnt vmcnt(0)
	s_andn2_b64 vcc, exec, s[18:19]
	s_cbranch_vccnz .LBB0_216
	ds_write_b128 v207, v[128:131] offset:8192
	ds_write_b128 v207, v[132:135] offset:17408
	ds_write_b128 v207, v[136:139] offset:26624
	s_branch .LBB0_216
.LBB0_245:
	v_xor_b32_e32 v207, 0x18000, v207
	v_mov_b32_e32 v0, v224
	s_nop 1
	v_permlane32_swap_b32_e32 v224, v0
	v_add_f32_e32 v0, v224, v0
	v_div_scale_f32 v2, s[4:5], v0, v0, 1.0
	v_rcp_f32_e32 v3, v2
	s_mov_b64 s[4:5], -1
	v_fma_f32 v4, -v2, v3, 1.0
	v_fmac_f32_e32 v3, v4, v3
	v_div_scale_f32 v4, vcc, 1.0, v0, 1.0
	v_mul_f32_e32 v5, v4, v3
	v_fma_f32 v6, -v2, v5, v4
	v_fmac_f32_e32 v5, v6, v3
	v_fma_f32 v2, -v2, v5, v4
	v_div_fmas_f32 v2, v2, v3, v5
	v_div_fixup_f32 v0, v2, v0, 1.0
	s_andn2_b64 vcc, exec, s[16:17]
	s_cbranch_vccz .LBB0_247
	s_andn2_b64 vcc, exec, s[4:5]
	s_cbranch_vccnz .LBB0_214
	s_branch .LBB0_248

; #define MFMA16(a, b, c) __builtin_amdgcn_mfma_f32_16x16x32_bf16((a), (b), (c), 0, 0, 0)
; DI void vm_wait0() { asm volatile("s_waitcnt vmcnt(0)" ::: "memory"); }
;   DI unsigned koff(int k) const { return (unsigned)((k >> 6) * EIN + (k & 63)); }
; DI void dma16(const void* g, unsigned char* l) { __builtin_amdgcn_global_load_lds((const unsigned*)g, (lds_u32_t*)(unsigned)(size_t)l, 16, 0, 0); }
; template <class AF, class EF>
; DI void gemm_run(unsigned char* lds, int wv, const AF& af, const bf16_t* __restrict__ Bt, int ldb, int M, int N, int K, const EF& ef, int blk_off) {
;     ...
;     for (int kt = 0; kt < nk; ++kt) {
;       unsigned char* cur = sBase + (kt & 1) * GST;
;       if (kt + 1 < nk) {
;         unsigned char* nxt = sBase + ((kt + 1) & 1) * GST;
;         const int k0 = (kt + 1) << 6;
; #pragma unroll
;         for (int i = 0; i < 4; ++i) {
;           dma16(Ab + aoff[i] + af.koff(k0 + cch), nxt + 32768 + (i * 512 + tid) * 16);
;           dma16(Bt + boff[i] + (unsigned)k0, nxt + (i * 512 + tid) * 16);
;         }
;       }
; #pragma unroll
;       for (int ks = 0; ks < 2; ++ks) {
;         bf16x8 wf[4], xf[8];
; #pragma unroll
;         for (int i = 0; i < 4; ++i) wf[i] = *(const bf16x8*)(cur + (wn * 64 + i * 16 + l15) * 128 + (((ks * 4 + q4) ^ swz) * 16));
; #pragma unroll
;         for (int j = 0; j < 8; ++j) xf[j] = *(const bf16x8*)(cur + 32768 + (wm * 128 + j * 16 + l15) * 128 + (((ks * 4 + q4) ^ swz) * 16));
; #pragma unroll
;         for (int i = 0; i < 4; ++i)
; #pragma unroll
;           for (int j = 0; j < 8; ++j) acc[i][j] = MFMA16(wf[i], xf[j], acc[i][j]);
;       }
;       vm_wait0();
;       __syncthreads();
;     }
.LBB0_262:
	s_add_i32 s100, s16, 0xffff0000
	s_and_b32 s100, s100, 0x10000
	v_add_u32_e32 v0, s100, v175
	v_add3_u32 v212, v0, v176, v177
	v_add3_u32 v0, v0, v178, v177
	ds_read_b128 v[130:133], v212 offset:8192
	ds_read_b128 v[180:183], v0 offset:40960
	ds_read_b128 v[184:187], v0 offset:43008
	ds_read_b128 v[188:191], v0 offset:45056
	ds_read_b128 v[192:195], v0 offset:47104
	ds_read_b128 v[196:199], v0 offset:49152
	ds_read_b128 v[200:203], v0 offset:51200
	ds_read_b128 v[204:207], v0 offset:53248
	ds_read_b128 v[208:211], v0 offset:55296
	s_cmpk_eq_i32 s4, 0x780
	s_cbranch_scc1 .Lmyg261_loop
	s_and_b32 s17, s16, 0x10000
	s_add_i32 s17, s17, 0
	s_add_i32 s18, s17, 0x2000
	s_add_i32 s17, s17, 0xa000
	v_add_u32_e32 v224, s17, v136
	v_lshl_add_u64 v[222:223], v[160:161], 0, s[4:5]
	v_readfirstlane_b32 s19, v224
	v_add_u32_e32 v224, s18, v136
	s_mov_b32 m0, s19
	v_readfirstlane_b32 s19, v224
	v_add_u32_e32 v224, s17, v138
	global_load_lds_dwordx4 v[222:223], off
	v_lshl_add_u64 v[222:223], v[152:153], 0, s[4:5]
	s_mov_b32 m0, s19
	v_readfirstlane_b32 s19, v224
	v_add_u32_e32 v224, s18, v138
	global_load_lds_dwordx4 v[222:223], off
	v_lshl_add_u64 v[222:223], v[158:159], 0, s[4:5]
	s_mov_b32 m0, s19
	v_readfirstlane_b32 s19, v224
	v_add_u32_e32 v224, s17, v140
	global_load_lds_dwordx4 v[222:223], off
	v_lshl_add_u64 v[222:223], v[150:151], 0, s[4:5]
	s_mov_b32 m0, s19
	v_readfirstlane_b32 s19, v224
	v_add_u32_e32 v224, s18, v140
	global_load_lds_dwordx4 v[222:223], off
	v_lshl_add_u64 v[222:223], v[156:157], 0, s[4:5]
	s_mov_b32 m0, s19
	v_readfirstlane_b32 s19, v224
	v_add_u32_e32 v224, s17, v142
	global_load_lds_dwordx4 v[222:223], off
	v_lshl_add_u64 v[222:223], v[148:149], 0, s[4:5]
	s_mov_b32 m0, s19
	v_readfirstlane_b32 s17, v224
	v_add_u32_e32 v224, s18, v142
	global_load_lds_dwordx4 v[222:223], off
	v_lshl_add_u64 v[222:223], v[154:155], 0, s[4:5]
	s_mov_b32 m0, s17
	v_readfirstlane_b32 s17, v224
	global_load_lds_dwordx4 v[222:223], off
	v_lshl_add_u64 v[222:223], v[146:147], 0, s[4:5]
	s_mov_b32 m0, s17
	s_nop 0
	global_load_lds_dwordx4 v[222:223], off
.Lmyg261_loop:
	s_waitcnt lgkmcnt(7)
	v_mfma_f32_16x16x32_bf16 v[126:129], v[130:133], v[180:183], v[126:129]
	ds_read_b128 v[226:229], v212 offset:10240
	s_waitcnt lgkmcnt(7)
	v_mfma_f32_16x16x32_bf16 v[118:121], v[130:133], v[184:187], v[118:121]
	s_waitcnt lgkmcnt(6)
	v_mfma_f32_16x16x32_bf16 v[110:113], v[130:133], v[188:191], v[110:113]
	s_waitcnt lgkmcnt(5)
	v_mfma_f32_16x16x32_bf16 v[102:105], v[130:133], v[192:195], v[102:105]
	s_waitcnt lgkmcnt(4)
	v_mfma_f32_16x16x32_bf16 v[94:97], v[130:133], v[196:199], v[94:97]
	s_waitcnt lgkmcnt(3)
	v_mfma_f32_16x16x32_bf16 v[86:89], v[130:133], v[200:203], v[86:89]
	s_waitcnt lgkmcnt(2)
	v_mfma_f32_16x16x32_bf16 v[78:81], v[130:133], v[204:207], v[78:81]
	s_waitcnt lgkmcnt(1)
	v_mfma_f32_16x16x32_bf16 v[70:73], v[130:133], v[208:211], v[70:73]
	s_waitcnt lgkmcnt(0)
	v_mfma_f32_16x16x32_bf16 v[122:125], v[226:229], v[180:183], v[122:125]
	ds_read_b128 v[130:133], v212 offset:12288
	v_mfma_f32_16x16x32_bf16 v[114:117], v[226:229], v[184:187], v[114:117]
	v_mfma_f32_16x16x32_bf16 v[106:109], v[226:229], v[188:191], v[106:109]
	v_mfma_f32_16x16x32_bf16 v[98:101], v[226:229], v[192:195], v[98:101]
	v_mfma_f32_16x16x32_bf16 v[90:93], v[226:229], v[196:199], v[90:93]
	v_mfma_f32_16x16x32_bf16 v[82:85], v[226:229], v[200:203], v[82:85]
	v_mfma_f32_16x16x32_bf16 v[74:77], v[226:229], v[204:207], v[74:77]
	v_mfma_f32_16x16x32_bf16 v[66:69], v[226:229], v[208:211], v[66:69]
	s_waitcnt lgkmcnt(0)
	v_mfma_f32_16x16x32_bf16 v[62:65], v[130:133], v[180:183], v[62:65]
	ds_read_b128 v[226:229], v212 offset:14336
	v_mfma_f32_16x16x32_bf16 v[54:57], v[130:133], v[184:187], v[54:57]
	v_add_u32_e32 v0, s100, v179
	v_mfma_f32_16x16x32_bf16 v[46:49], v[130:133], v[188:191], v[46:49]
	v_add3_u32 v212, v0, v176, v177
	v_mfma_f32_16x16x32_bf16 v[38:41], v[130:133], v[192:195], v[38:41]
	v_add3_u32 v0, v0, v178, v177
	v_mfma_f32_16x16x32_bf16 v[30:33], v[130:133], v[196:199], v[30:33]
	v_mfma_f32_16x16x32_bf16 v[22:25], v[130:133], v[200:203], v[22:25]
	v_mfma_f32_16x16x32_bf16 v[14:17], v[130:133], v[204:207], v[14:17]
	v_mfma_f32_16x16x32_bf16 v[2:5], v[130:133], v[208:211], v[2:5]
	s_waitcnt lgkmcnt(0)
	v_mfma_f32_16x16x32_bf16 v[58:61], v[226:229], v[180:183], v[58:61]
	ds_read_b128 v[130:133], v212 offset:8192
	ds_read_b128 v[180:183], v0 offset:40960
	v_mfma_f32_16x16x32_bf16 v[50:53], v[226:229], v[184:187], v[50:53]
	ds_read_b128 v[184:187], v0 offset:43008
	v_mfma_f32_16x16x32_bf16 v[42:45], v[226:229], v[188:191], v[42:45]
	ds_read_b128 v[188:191], v0 offset:45056
	v_mfma_f32_16x16x32_bf16 v[34:37], v[226:229], v[192:195], v[34:37]
	ds_read_b128 v[192:195], v0 offset:47104
	v_mfma_f32_16x16x32_bf16 v[26:29], v[226:229], v[196:199], v[26:29]
	ds_read_b128 v[196:199], v0 offset:49152
	v_mfma_f32_16x16x32_bf16 v[18:21], v[226:229], v[200:203], v[18:21]
	ds_read_b128 v[200:203], v0 offset:51200
	v_mfma_f32_16x16x32_bf16 v[10:13], v[226:229], v[204:207], v[10:13]
	ds_read_b128 v[204:207], v0 offset:53248
	v_mfma_f32_16x16x32_bf16 v[6:9], v[226:229], v[208:211], v[6:9]
	ds_read_b128 v[208:211], v0 offset:55296
	s_waitcnt lgkmcnt(7)
	v_mfma_f32_16x16x32_bf16 v[126:129], v[130:133], v[180:183], v[126:129]
	ds_read_b128 v[226:229], v212 offset:10240
	s_waitcnt lgkmcnt(7)
; #define MFMA16(a, b, c) __builtin_amdgcn_mfma_f32_16x16x32_bf16((a), (b), (c), 0, 0, 0)
; DI void vm_wait0() { asm volatile("s_waitcnt vmcnt(0)" ::: "memory"); }
;   DI unsigned koff(int k) const { return (unsigned)((k >> 6) * EIN + (k & 63)); }
; DI void dma16(const void* g, unsigned char* l) { __builtin_amdgcn_global_load_lds((const unsigned*)g, (lds_u32_t*)(unsigned)(size_t)l, 16, 0, 0); }
; template <class AF, class EF>
; DI void gemm_run(unsigned char* lds, int wv, const AF& af, const bf16_t* __restrict__ Bt, int ldb, int M, int N, int K, const EF& ef, int blk_off) {
;     ...
;     for (int kt = 0; kt < nk; ++kt) {
;       unsigned char* cur = sBase + (kt & 1) * GST;
;       if (kt + 1 < nk) {
;         unsigned char* nxt = sBase + ((kt + 1) & 1) * GST;
;         const int k0 = (kt + 1) << 6;
; #pragma unroll
;         for (int i = 0; i < 4; ++i) {
;           dma16(Ab + aoff[i] + af.koff(k0 + cch), nxt + 32768 + (i * 512 + tid) * 16);
;           dma16(Bt + boff[i] + (unsigned)k0, nxt + (i * 512 + tid) * 16);
;         }
;       }
; #pragma unroll
;       for (int ks = 0; ks < 2; ++ks) {
;         bf16x8 wf[4], xf[8];
; #pragma unroll
;         for (int i = 0; i < 4; ++i) wf[i] = *(const bf16x8*)(cur + (wn * 64 + i * 16 + l15) * 128 + (((ks * 4 + q4) ^ swz) * 16));
; #pragma unroll
;         for (int j = 0; j < 8; ++j) xf[j] = *(const bf16x8*)(cur + 32768 + (wm * 128 + j * 16 + l15) * 128 + (((ks * 4 + q4) ^ swz) * 16));
; #pragma unroll
;         for (int i = 0; i < 4; ++i)
; #pragma unroll
;           for (int j = 0; j < 8; ++j) acc[i][j] = MFMA16(wf[i], xf[j], acc[i][j]);
;       }
;       vm_wait0();
;       __syncthreads();
;     }
	v_mfma_f32_16x16x32_bf16 v[118:121], v[130:133], v[184:187], v[118:121]
	s_waitcnt lgkmcnt(6)
	v_mfma_f32_16x16x32_bf16 v[110:113], v[130:133], v[188:191], v[110:113]
	s_waitcnt lgkmcnt(5)
	v_mfma_f32_16x16x32_bf16 v[102:105], v[130:133], v[192:195], v[102:105]
	s_waitcnt lgkmcnt(4)
	v_mfma_f32_16x16x32_bf16 v[94:97], v[130:133], v[196:199], v[94:97]
	s_waitcnt lgkmcnt(3)
	v_mfma_f32_16x16x32_bf16 v[86:89], v[130:133], v[200:203], v[86:89]
	s_waitcnt lgkmcnt(2)
	v_mfma_f32_16x16x32_bf16 v[78:81], v[130:133], v[204:207], v[78:81]
	s_waitcnt lgkmcnt(1)
	v_mfma_f32_16x16x32_bf16 v[70:73], v[130:133], v[208:211], v[70:73]
	s_waitcnt lgkmcnt(0)
	v_mfma_f32_16x16x32_bf16 v[122:125], v[226:229], v[180:183], v[122:125]
	ds_read_b128 v[130:133], v212 offset:12288
	v_mfma_f32_16x16x32_bf16 v[114:117], v[226:229], v[184:187], v[114:117]
	v_mfma_f32_16x16x32_bf16 v[106:109], v[226:229], v[188:191], v[106:109]
	v_mfma_f32_16x16x32_bf16 v[98:101], v[226:229], v[192:195], v[98:101]
	v_mfma_f32_16x16x32_bf16 v[90:93], v[226:229], v[196:199], v[90:93]
	v_mfma_f32_16x16x32_bf16 v[82:85], v[226:229], v[200:203], v[82:85]
	v_mfma_f32_16x16x32_bf16 v[74:77], v[226:229], v[204:207], v[74:77]
	v_mfma_f32_16x16x32_bf16 v[66:69], v[226:229], v[208:211], v[66:69]
	s_waitcnt lgkmcnt(0)
	v_mfma_f32_16x16x32_bf16 v[62:65], v[130:133], v[180:183], v[62:65]
	ds_read_b128 v[226:229], v212 offset:14336
	v_mfma_f32_16x16x32_bf16 v[54:57], v[130:133], v[184:187], v[54:57]
	v_mfma_f32_16x16x32_bf16 v[46:49], v[130:133], v[188:191], v[46:49]
	v_mfma_f32_16x16x32_bf16 v[38:41], v[130:133], v[192:195], v[38:41]
	v_mfma_f32_16x16x32_bf16 v[30:33], v[130:133], v[196:199], v[30:33]
	v_mfma_f32_16x16x32_bf16 v[22:25], v[130:133], v[200:203], v[22:25]
	v_mfma_f32_16x16x32_bf16 v[14:17], v[130:133], v[204:207], v[14:17]
	v_mfma_f32_16x16x32_bf16 v[2:5], v[130:133], v[208:211], v[2:5]
	s_waitcnt vmcnt(0) lgkmcnt(0)
	s_barrier
	s_add_u32 s4, s4, 0x80
	s_addc_u32 s5, s5, 0
	s_add_i32 s16, s16, 0x10000
	s_cmpk_eq_i32 s4, 0x800
	s_cbranch_scc1 .Lmyg261_tail
	s_add_i32 s100, s16, 0xffff0000
	s_and_b32 s100, s100, 0x10000
	v_add_u32_e32 v0, s100, v175
	v_add3_u32 v212, v0, v176, v177
	v_add3_u32 v0, v0, v178, v177
	s_cmpk_eq_i32 s4, 0x780
	v_mfma_f32_16x16x32_bf16 v[58:61], v[226:229], v[180:183], v[58:61]
	ds_read_b128 v[130:133], v212 offset:8192
	ds_read_b128 v[180:183], v0 offset:40960
	v_mfma_f32_16x16x32_bf16 v[50:53], v[226:229], v[184:187], v[50:53]
	ds_read_b128 v[184:187], v0 offset:43008
	v_mfma_f32_16x16x32_bf16 v[42:45], v[226:229], v[188:191], v[42:45]
	ds_read_b128 v[188:191], v0 offset:45056
	v_mfma_f32_16x16x32_bf16 v[34:37], v[226:229], v[192:195], v[34:37]
	ds_read_b128 v[192:195], v0 offset:47104
	v_mfma_f32_16x16x32_bf16 v[26:29], v[226:229], v[196:199], v[26:29]
	ds_read_b128 v[196:199], v0 offset:49152
	v_mfma_f32_16x16x32_bf16 v[18:21], v[226:229], v[200:203], v[18:21]
	ds_read_b128 v[200:203], v0 offset:51200
	v_mfma_f32_16x16x32_bf16 v[10:13], v[226:229], v[204:207], v[10:13]
	ds_read_b128 v[204:207], v0 offset:53248
	v_mfma_f32_16x16x32_bf16 v[6:9], v[226:229], v[208:211], v[6:9]
	ds_read_b128 v[208:211], v0 offset:55296
	s_cbranch_scc1 .Lmyg261_loop
	s_and_b32 s17, s16, 0x10000
	s_add_i32 s17, s17, 0
	s_add_i32 s18, s17, 0x2000
	s_add_i32 s17, s17, 0xa000
	v_add_u32_e32 v224, s17, v136
	v_lshl_add_u64 v[222:223], v[160:161], 0, s[4:5]
	v_readfirstlane_b32 s19, v224
	v_add_u32_e32 v224, s18, v136
	s_mov_b32 m0, s19
	v_readfirstlane_b32 s19, v224
	v_add_u32_e32 v224, s17, v138
	global_load_lds_dwordx4 v[222:223], off
	v_lshl_add_u64 v[222:223], v[152:153], 0, s[4:5]
	s_mov_b32 m0, s19
	v_readfirstlane_b32 s19, v224
	v_add_u32_e32 v224, s18, v138
	global_load_lds_dwordx4 v[222:223], off
	v_lshl_add_u64 v[222:223], v[158:159], 0, s[4:5]
	s_mov_b32 m0, s19
	v_readfirstlane_b32 s19, v224
	v_add_u32_e32 v224, s17, v140
	global_load_lds_dwordx4 v[222:223], off
	v_lshl_add_u64 v[222:223], v[150:151], 0, s[4:5]
	s_mov_b32 m0, s19
	v_readfirstlane_b32 s19, v224
	v_add_u32_e32 v224, s18, v140
	global_load_lds_dwordx4 v[222:223], off
	v_lshl_add_u64 v[222:223], v[156:157], 0, s[4:5]
	s_mov_b32 m0, s19
	v_readfirstlane_b32 s19, v224
	v_add_u32_e32 v224, s17, v142
	global_load_lds_dwordx4 v[222:223], off
	v_lshl_add_u64 v[222:223], v[148:149], 0, s[4:5]
	s_mov_b32 m0, s19
	v_readfirstlane_b32 s17, v224
	v_add_u32_e32 v224, s18, v142
	global_load_lds_dwordx4 v[222:223], off
	v_lshl_add_u64 v[222:223], v[154:155], 0, s[4:5]
	s_mov_b32 m0, s17
	v_readfirstlane_b32 s17, v224
	global_load_lds_dwordx4 v[222:223], off
	v_lshl_add_u64 v[222:223], v[146:147], 0, s[4:5]
	s_mov_b32 m0, s17
	s_nop 0
	global_load_lds_dwordx4 v[222:223], off
	s_branch .Lmyg261_loop
.Lmyg261_tail:
	v_mfma_f32_16x16x32_bf16 v[58:61], v[226:229], v[180:183], v[58:61]
	v_mfma_f32_16x16x32_bf16 v[50:53], v[226:229], v[184:187], v[50:53]
	v_mfma_f32_16x16x32_bf16 v[42:45], v[226:229], v[188:191], v[42:45]
	v_mfma_f32_16x16x32_bf16 v[34:37], v[226:229], v[192:195], v[34:37]
	v_mfma_f32_16x16x32_bf16 v[26:29], v[226:229], v[196:199], v[26:29]
	v_mfma_f32_16x16x32_bf16 v[18:21], v[226:229], v[200:203], v[18:21]
	v_mfma_f32_16x16x32_bf16 v[10:13], v[226:229], v[204:207], v[10:13]
	v_mfma_f32_16x16x32_bf16 v[6:9], v[226:229], v[208:211], v[6:9]
	s_branch .LBB0_264

; #define MFMA16(a, b, c) __builtin_amdgcn_mfma_f32_16x16x32_bf16((a), (b), (c), 0, 0, 0)
; DI void vm_wait0() { asm volatile("s_waitcnt vmcnt(0)" ::: "memory"); }
;   DI unsigned koff(int k) const { return (unsigned)((k >> 6) * EIN + (k & 63)); }
; DI void dma16(const void* g, unsigned char* l) { __builtin_amdgcn_global_load_lds((const unsigned*)g, (lds_u32_t*)(unsigned)(size_t)l, 16, 0, 0); }
; template <class AF, class EF>
; DI void gemm_run(unsigned char* lds, int wv, const AF& af, const bf16_t* __restrict__ Bt, int ldb, int M, int N, int K, const EF& ef, int blk_off) {
;     ...
;     for (int kt = 0; kt < nk; ++kt) {
;       unsigned char* cur = sBase + (kt & 1) * GST;
;       if (kt + 1 < nk) {
;         unsigned char* nxt = sBase + ((kt + 1) & 1) * GST;
;         const int k0 = (kt + 1) << 6;
; #pragma unroll
;         for (int i = 0; i < 4; ++i) {
;           dma16(Ab + aoff[i] + af.koff(k0 + cch), nxt + 32768 + (i * 512 + tid) * 16);
;           dma16(Bt + boff[i] + (unsigned)k0, nxt + (i * 512 + tid) * 16);
;         }
;       }
; #pragma unroll
;       for (int ks = 0; ks < 2; ++ks) {
;         bf16x8 wf[4], xf[8];
; #pragma unroll
;         for (int i = 0; i < 4; ++i) wf[i] = *(const bf16x8*)(cur + (wn * 64 + i * 16 + l15) * 128 + (((ks * 4 + q4) ^ swz) * 16));
; #pragma unroll
;         for (int j = 0; j < 8; ++j) xf[j] = *(const bf16x8*)(cur + 32768 + (wm * 128 + j * 16 + l15) * 128 + (((ks * 4 + q4) ^ swz) * 16));
; #pragma unroll
;         for (int i = 0; i < 4; ++i)
; #pragma unroll
;           for (int j = 0; j < 8; ++j) acc[i][j] = MFMA16(wf[i], xf[j], acc[i][j]);
;       }
;       vm_wait0();
;       __syncthreads();
;     }
.LBB0_1246:
	s_add_i32 s100, s20, 0xffff0000
	s_and_b32 s100, s100, 0x10000
	v_add_u32_e32 v0, s100, v179
	v_add3_u32 v212, v0, v180, v181
	v_add3_u32 v0, v0, v182, v181
	ds_read_b128 v[130:133], v212 offset:8192
	ds_read_b128 v[184:187], v0 offset:43008
	ds_read_b128 v[134:137], v0 offset:40960
	ds_read_b128 v[188:191], v0 offset:45056
	ds_read_b128 v[192:195], v0 offset:47104
	ds_read_b128 v[196:199], v0 offset:49152
	ds_read_b128 v[200:203], v0 offset:51200
	ds_read_b128 v[204:207], v0 offset:53248
	ds_read_b128 v[208:211], v0 offset:55296
	s_cmp_gt_u32 s19, 14
	s_cbranch_scc1 .Lmyg1245_loop
	s_and_b32 s21, s20, 0x10000
	s_add_i32 s21, s21, 0
	s_add_i32 s22, s21, 0x2000
	s_add_i32 s21, s21, 0xa000
	v_add_u32_e32 v224, s21, v140
	v_lshl_add_u64 v[222:223], v[166:167], 0, s[14:15]
	v_readfirstlane_b32 s23, v224
	v_add_u32_e32 v224, s22, v140
	s_mov_b32 m0, s23
	v_readfirstlane_b32 s23, v224
	v_add_u32_e32 v224, s21, v142
	global_load_lds_dwordx4 v[222:223], off
	v_lshl_add_u64 v[222:223], v[156:157], 0, s[14:15]
	s_mov_b32 m0, s23
	v_readfirstlane_b32 s23, v224
	v_add_u32_e32 v224, s22, v142
	global_load_lds_dwordx4 v[222:223], off
	v_lshl_add_u64 v[222:223], v[164:165], 0, s[14:15]
	s_mov_b32 m0, s23
	v_readfirstlane_b32 s23, v224
	v_add_u32_e32 v224, s21, v144
	global_load_lds_dwordx4 v[222:223], off
	v_lshl_add_u64 v[222:223], v[154:155], 0, s[14:15]
	s_mov_b32 m0, s23
	v_readfirstlane_b32 s23, v224
	v_add_u32_e32 v224, s22, v144
	global_load_lds_dwordx4 v[222:223], off
	v_lshl_add_u64 v[222:223], v[160:161], 0, s[14:15]
	s_mov_b32 m0, s23
	v_readfirstlane_b32 s23, v224
	v_add_u32_e32 v224, s21, v146
	global_load_lds_dwordx4 v[222:223], off
	v_lshl_add_u64 v[222:223], v[152:153], 0, s[14:15]
	s_mov_b32 m0, s23
	v_readfirstlane_b32 s21, v224
	v_add_u32_e32 v224, s22, v146
	global_load_lds_dwordx4 v[222:223], off
	v_lshl_add_u64 v[222:223], v[158:159], 0, s[14:15]
	s_mov_b32 m0, s21
	v_readfirstlane_b32 s21, v224
	global_load_lds_dwordx4 v[222:223], off
	v_lshl_add_u64 v[222:223], v[150:151], 0, s[14:15]
	s_mov_b32 m0, s21
	s_nop 0
	global_load_lds_dwordx4 v[222:223], off
.Lmyg1245_loop:
	s_waitcnt lgkmcnt(7)
	v_mfma_f32_16x16x32_bf16 v[118:121], v[130:133], v[184:187], v[118:121]
	ds_read_b128 v[226:229], v212 offset:10240
	s_waitcnt lgkmcnt(7)
	v_mfma_f32_16x16x32_bf16 v[126:129], v[130:133], v[134:137], v[126:129]
	s_waitcnt lgkmcnt(6)
	v_mfma_f32_16x16x32_bf16 v[110:113], v[130:133], v[188:191], v[110:113]
	s_waitcnt lgkmcnt(5)
	v_mfma_f32_16x16x32_bf16 v[102:105], v[130:133], v[192:195], v[102:105]
	s_waitcnt lgkmcnt(4)
	v_mfma_f32_16x16x32_bf16 v[94:97], v[130:133], v[196:199], v[94:97]
	s_waitcnt lgkmcnt(3)
	v_mfma_f32_16x16x32_bf16 v[86:89], v[130:133], v[200:203], v[86:89]
	s_waitcnt lgkmcnt(2)
	v_mfma_f32_16x16x32_bf16 v[78:81], v[130:133], v[204:207], v[78:81]
	s_waitcnt lgkmcnt(1)
	v_mfma_f32_16x16x32_bf16 v[70:73], v[130:133], v[208:211], v[70:73]
	s_waitcnt lgkmcnt(0)
	v_mfma_f32_16x16x32_bf16 v[122:125], v[226:229], v[134:137], v[122:125]
	ds_read_b128 v[130:133], v212 offset:12288
	v_mfma_f32_16x16x32_bf16 v[114:117], v[226:229], v[184:187], v[114:117]
	v_mfma_f32_16x16x32_bf16 v[106:109], v[226:229], v[188:191], v[106:109]
	v_mfma_f32_16x16x32_bf16 v[98:101], v[226:229], v[192:195], v[98:101]
	v_mfma_f32_16x16x32_bf16 v[90:93], v[226:229], v[196:199], v[90:93]
	v_mfma_f32_16x16x32_bf16 v[82:85], v[226:229], v[200:203], v[82:85]
	v_mfma_f32_16x16x32_bf16 v[74:77], v[226:229], v[204:207], v[74:77]
	v_mfma_f32_16x16x32_bf16 v[66:69], v[226:229], v[208:211], v[66:69]
	s_waitcnt lgkmcnt(0)
	v_mfma_f32_16x16x32_bf16 v[58:61], v[130:133], v[134:137], v[58:61]
	ds_read_b128 v[226:229], v212 offset:14336
	v_mfma_f32_16x16x32_bf16 v[50:53], v[130:133], v[184:187], v[50:53]
	v_add_u32_e32 v0, s100, v183
	v_mfma_f32_16x16x32_bf16 v[42:45], v[130:133], v[188:191], v[42:45]
	v_add3_u32 v212, v0, v180, v181
	v_mfma_f32_16x16x32_bf16 v[30:33], v[130:133], v[192:195], v[30:33]
	v_add3_u32 v0, v0, v182, v181
	v_mfma_f32_16x16x32_bf16 v[14:17], v[130:133], v[196:199], v[14:17]
	v_mfma_f32_16x16x32_bf16 v[10:13], v[130:133], v[200:203], v[10:13]
	v_mfma_f32_16x16x32_bf16 v[6:9], v[130:133], v[204:207], v[6:9]
	v_mfma_f32_16x16x32_bf16 v[2:5], v[130:133], v[208:211], v[2:5]
	s_waitcnt lgkmcnt(0)
	v_mfma_f32_16x16x32_bf16 v[54:57], v[226:229], v[184:187], v[54:57]
	ds_read_b128 v[130:133], v212 offset:8192
	ds_read_b128 v[184:187], v0 offset:43008
	v_mfma_f32_16x16x32_bf16 v[62:65], v[226:229], v[134:137], v[62:65]
	ds_read_b128 v[134:137], v0 offset:40960
	v_mfma_f32_16x16x32_bf16 v[46:49], v[226:229], v[188:191], v[46:49]
	ds_read_b128 v[188:191], v0 offset:45056
	v_mfma_f32_16x16x32_bf16 v[38:41], v[226:229], v[192:195], v[38:41]
	ds_read_b128 v[192:195], v0 offset:47104
	v_mfma_f32_16x16x32_bf16 v[26:29], v[226:229], v[196:199], v[26:29]
	ds_read_b128 v[196:199], v0 offset:49152
	v_mfma_f32_16x16x32_bf16 v[22:25], v[226:229], v[200:203], v[22:25]
	ds_read_b128 v[200:203], v0 offset:51200
	v_mfma_f32_16x16x32_bf16 v[34:37], v[226:229], v[204:207], v[34:37]
	ds_read_b128 v[204:207], v0 offset:53248
	v_mfma_f32_16x16x32_bf16 v[18:21], v[226:229], v[208:211], v[18:21]
	ds_read_b128 v[208:211], v0 offset:55296
	s_waitcnt lgkmcnt(7)
	v_mfma_f32_16x16x32_bf16 v[118:121], v[130:133], v[184:187], v[118:121]
	ds_read_b128 v[226:229], v212 offset:10240
	s_waitcnt lgkmcnt(7)
; #define MFMA16(a, b, c) __builtin_amdgcn_mfma_f32_16x16x32_bf16((a), (b), (c), 0, 0, 0)
; DI void vm_wait0() { asm volatile("s_waitcnt vmcnt(0)" ::: "memory"); }
;   DI unsigned koff(int k) const { return (unsigned)((k >> 6) * EIN + (k & 63)); }
; DI void dma16(const void* g, unsigned char* l) { __builtin_amdgcn_global_load_lds((const unsigned*)g, (lds_u32_t*)(unsigned)(size_t)l, 16, 0, 0); }
; template <class AF, class EF>
; DI void gemm_run(unsigned char* lds, int wv, const AF& af, const bf16_t* __restrict__ Bt, int ldb, int M, int N, int K, const EF& ef, int blk_off) {
;     ...
;     for (int kt = 0; kt < nk; ++kt) {
;       unsigned char* cur = sBase + (kt & 1) * GST;
;       if (kt + 1 < nk) {
;         unsigned char* nxt = sBase + ((kt + 1) & 1) * GST;
;         const int k0 = (kt + 1) << 6;
; #pragma unroll
;         for (int i = 0; i < 4; ++i) {
;           dma16(Ab + aoff[i] + af.koff(k0 + cch), nxt + 32768 + (i * 512 + tid) * 16);
;           dma16(Bt + boff[i] + (unsigned)k0, nxt + (i * 512 + tid) * 16);
;         }
;       }
; #pragma unroll
;       for (int ks = 0; ks < 2; ++ks) {
;         bf16x8 wf[4], xf[8];
; #pragma unroll
;         for (int i = 0; i < 4; ++i) wf[i] = *(const bf16x8*)(cur + (wn * 64 + i * 16 + l15) * 128 + (((ks * 4 + q4) ^ swz) * 16));
; #pragma unroll
;         for (int j = 0; j < 8; ++j) xf[j] = *(const bf16x8*)(cur + 32768 + (wm * 128 + j * 16 + l15) * 128 + (((ks * 4 + q4) ^ swz) * 16));
; #pragma unroll
;         for (int i = 0; i < 4; ++i)
; #pragma unroll
;           for (int j = 0; j < 8; ++j) acc[i][j] = MFMA16(wf[i], xf[j], acc[i][j]);
;       }
;       vm_wait0();
;       __syncthreads();
;     }
	v_mfma_f32_16x16x32_bf16 v[126:129], v[130:133], v[134:137], v[126:129]
	s_waitcnt lgkmcnt(6)
	v_mfma_f32_16x16x32_bf16 v[110:113], v[130:133], v[188:191], v[110:113]
	s_waitcnt lgkmcnt(5)
	v_mfma_f32_16x16x32_bf16 v[102:105], v[130:133], v[192:195], v[102:105]
	s_waitcnt lgkmcnt(4)
	v_mfma_f32_16x16x32_bf16 v[94:97], v[130:133], v[196:199], v[94:97]
	s_waitcnt lgkmcnt(3)
	v_mfma_f32_16x16x32_bf16 v[86:89], v[130:133], v[200:203], v[86:89]
	s_waitcnt lgkmcnt(2)
	v_mfma_f32_16x16x32_bf16 v[78:81], v[130:133], v[204:207], v[78:81]
	s_waitcnt lgkmcnt(1)
	v_mfma_f32_16x16x32_bf16 v[70:73], v[130:133], v[208:211], v[70:73]
	s_waitcnt lgkmcnt(0)
	v_mfma_f32_16x16x32_bf16 v[122:125], v[226:229], v[134:137], v[122:125]
	ds_read_b128 v[130:133], v212 offset:12288
	v_mfma_f32_16x16x32_bf16 v[114:117], v[226:229], v[184:187], v[114:117]
	v_mfma_f32_16x16x32_bf16 v[106:109], v[226:229], v[188:191], v[106:109]
	v_mfma_f32_16x16x32_bf16 v[98:101], v[226:229], v[192:195], v[98:101]
	v_mfma_f32_16x16x32_bf16 v[90:93], v[226:229], v[196:199], v[90:93]
	v_mfma_f32_16x16x32_bf16 v[82:85], v[226:229], v[200:203], v[82:85]
	v_mfma_f32_16x16x32_bf16 v[74:77], v[226:229], v[204:207], v[74:77]
	v_mfma_f32_16x16x32_bf16 v[66:69], v[226:229], v[208:211], v[66:69]
	s_waitcnt lgkmcnt(0)
	v_mfma_f32_16x16x32_bf16 v[58:61], v[130:133], v[134:137], v[58:61]
	ds_read_b128 v[226:229], v212 offset:14336
	v_mfma_f32_16x16x32_bf16 v[50:53], v[130:133], v[184:187], v[50:53]
	v_mfma_f32_16x16x32_bf16 v[42:45], v[130:133], v[188:191], v[42:45]
	v_mfma_f32_16x16x32_bf16 v[30:33], v[130:133], v[192:195], v[30:33]
	v_mfma_f32_16x16x32_bf16 v[14:17], v[130:133], v[196:199], v[14:17]
	v_mfma_f32_16x16x32_bf16 v[10:13], v[130:133], v[200:203], v[10:13]
	v_mfma_f32_16x16x32_bf16 v[6:9], v[130:133], v[204:207], v[6:9]
	v_mfma_f32_16x16x32_bf16 v[2:5], v[130:133], v[208:211], v[2:5]
	s_waitcnt vmcnt(0) lgkmcnt(0)
	s_barrier
	s_add_u32 s14, s14, 0x80
	s_addc_u32 s15, s15, 0
	s_add_i32 s20, s20, 0x10000
	s_add_i32 s19, s19, 1
	s_cmpk_eq_i32 s14, 0x800
	s_cbranch_scc1 .Lmyg1245_tail
	s_add_i32 s100, s20, 0xffff0000
	s_and_b32 s100, s100, 0x10000
	v_add_u32_e32 v0, s100, v179
	v_add3_u32 v212, v0, v180, v181
	v_add3_u32 v0, v0, v182, v181
	s_cmp_gt_u32 s19, 14
	v_mfma_f32_16x16x32_bf16 v[54:57], v[226:229], v[184:187], v[54:57]
	ds_read_b128 v[130:133], v212 offset:8192
	ds_read_b128 v[184:187], v0 offset:43008
	v_mfma_f32_16x16x32_bf16 v[62:65], v[226:229], v[134:137], v[62:65]
	ds_read_b128 v[134:137], v0 offset:40960
	v_mfma_f32_16x16x32_bf16 v[46:49], v[226:229], v[188:191], v[46:49]
	ds_read_b128 v[188:191], v0 offset:45056
	v_mfma_f32_16x16x32_bf16 v[38:41], v[226:229], v[192:195], v[38:41]
	ds_read_b128 v[192:195], v0 offset:47104
	v_mfma_f32_16x16x32_bf16 v[26:29], v[226:229], v[196:199], v[26:29]
	ds_read_b128 v[196:199], v0 offset:49152
	v_mfma_f32_16x16x32_bf16 v[22:25], v[226:229], v[200:203], v[22:25]
	ds_read_b128 v[200:203], v0 offset:51200
	v_mfma_f32_16x16x32_bf16 v[34:37], v[226:229], v[204:207], v[34:37]
	ds_read_b128 v[204:207], v0 offset:53248
	v_mfma_f32_16x16x32_bf16 v[18:21], v[226:229], v[208:211], v[18:21]
	ds_read_b128 v[208:211], v0 offset:55296
	s_cbranch_scc1 .Lmyg1245_loop
	s_and_b32 s21, s20, 0x10000
	s_add_i32 s21, s21, 0
	s_add_i32 s22, s21, 0x2000
	s_add_i32 s21, s21, 0xa000
	v_add_u32_e32 v224, s21, v140
	v_lshl_add_u64 v[222:223], v[166:167], 0, s[14:15]
	v_readfirstlane_b32 s23, v224
	v_add_u32_e32 v224, s22, v140
	s_mov_b32 m0, s23
	v_readfirstlane_b32 s23, v224
	v_add_u32_e32 v224, s21, v142
	global_load_lds_dwordx4 v[222:223], off
	v_lshl_add_u64 v[222:223], v[156:157], 0, s[14:15]
	s_mov_b32 m0, s23
	v_readfirstlane_b32 s23, v224
	v_add_u32_e32 v224, s22, v142
	global_load_lds_dwordx4 v[222:223], off
	v_lshl_add_u64 v[222:223], v[164:165], 0, s[14:15]
	s_mov_b32 m0, s23
	v_readfirstlane_b32 s23, v224
	v_add_u32_e32 v224, s21, v144
	global_load_lds_dwordx4 v[222:223], off
	v_lshl_add_u64 v[222:223], v[154:155], 0, s[14:15]
	s_mov_b32 m0, s23
	v_readfirstlane_b32 s23, v224
	v_add_u32_e32 v224, s22, v144
	global_load_lds_dwordx4 v[222:223], off
	v_lshl_add_u64 v[222:223], v[160:161], 0, s[14:15]
	s_mov_b32 m0, s23
	v_readfirstlane_b32 s23, v224
	v_add_u32_e32 v224, s21, v146
	global_load_lds_dwordx4 v[222:223], off
	v_lshl_add_u64 v[222:223], v[152:153], 0, s[14:15]
	s_mov_b32 m0, s23
	v_readfirstlane_b32 s21, v224
	v_add_u32_e32 v224, s22, v146
	global_load_lds_dwordx4 v[222:223], off
	v_lshl_add_u64 v[222:223], v[158:159], 0, s[14:15]
	s_mov_b32 m0, s21
	v_readfirstlane_b32 s21, v224
	global_load_lds_dwordx4 v[222:223], off
	v_lshl_add_u64 v[222:223], v[150:151], 0, s[14:15]
	s_mov_b32 m0, s21
	s_nop 0
	global_load_lds_dwordx4 v[222:223], off
	s_branch .Lmyg1245_loop
.Lmyg1245_tail:
	v_mfma_f32_16x16x32_bf16 v[54:57], v[226:229], v[184:187], v[54:57]
	v_mfma_f32_16x16x32_bf16 v[62:65], v[226:229], v[134:137], v[62:65]
	v_mfma_f32_16x16x32_bf16 v[46:49], v[226:229], v[188:191], v[46:49]
	v_mfma_f32_16x16x32_bf16 v[38:41], v[226:229], v[192:195], v[38:41]
	v_mfma_f32_16x16x32_bf16 v[26:29], v[226:229], v[196:199], v[26:29]
	v_mfma_f32_16x16x32_bf16 v[22:25], v[226:229], v[200:203], v[22:25]
	v_mfma_f32_16x16x32_bf16 v[34:37], v[226:229], v[204:207], v[34:37]
	v_mfma_f32_16x16x32_bf16 v[18:21], v[226:229], v[208:211], v[18:21]
	s_branch .LBB0_1243

; #define MFMA16(a, b, c) __builtin_amdgcn_mfma_f32_16x16x32_bf16((a), (b), (c), 0, 0, 0)
; DI void vm_wait0() { asm volatile("s_waitcnt vmcnt(0)" ::: "memory"); }
;   DI unsigned koff(int k) const { return (unsigned)((k >> 6) * EIN + (k & 63)); }
; DI void dma16(const void* g, unsigned char* l) { __builtin_amdgcn_global_load_lds((const unsigned*)g, (lds_u32_t*)(unsigned)(size_t)l, 16, 0, 0); }
; template <class AF, class EF>
; DI void gemm_run(unsigned char* lds, int wv, const AF& af, const bf16_t* __restrict__ Bt, int ldb, int M, int N, int K, const EF& ef, int blk_off) {
;     ...
;     for (int kt = 0; kt < nk; ++kt) {
;       unsigned char* cur = sBase + (kt & 1) * GST;
;       if (kt + 1 < nk) {
;         unsigned char* nxt = sBase + ((kt + 1) & 1) * GST;
;         const int k0 = (kt + 1) << 6;
; #pragma unroll
;         for (int i = 0; i < 4; ++i) {
;           dma16(Ab + aoff[i] + af.koff(k0 + cch), nxt + 32768 + (i * 512 + tid) * 16);
;           dma16(Bt + boff[i] + (unsigned)k0, nxt + (i * 512 + tid) * 16);
;         }
;       }
; #pragma unroll
;       for (int ks = 0; ks < 2; ++ks) {
;         bf16x8 wf[4], xf[8];
; #pragma unroll
;         for (int i = 0; i < 4; ++i) wf[i] = *(const bf16x8*)(cur + (wn * 64 + i * 16 + l15) * 128 + (((ks * 4 + q4) ^ swz) * 16));
; #pragma unroll
;         for (int j = 0; j < 8; ++j) xf[j] = *(const bf16x8*)(cur + 32768 + (wm * 128 + j * 16 + l15) * 128 + (((ks * 4 + q4) ^ swz) * 16));
; #pragma unroll
;         for (int i = 0; i < 4; ++i)
; #pragma unroll
;           for (int j = 0; j < 8; ++j) acc[i][j] = MFMA16(wf[i], xf[j], acc[i][j]);
;       }
;       vm_wait0();
;       __syncthreads();
;     }
.LBB0_1268:
	s_add_i32 s100, s15, 0xffff0000
	s_and_b32 s100, s100, 0x10000
	v_add_u32_e32 v0, s100, v174
	v_add3_u32 v179, v0, v175, v176
	v_add3_u32 v0, v0, v177, v176
	ds_read_b128 v[130:133], v179 offset:8192
	ds_read_b128 v[180:183], v0 offset:40960
	ds_read_b128 v[184:187], v0 offset:43008
	ds_read_b128 v[188:191], v0 offset:45056
	ds_read_b128 v[192:195], v0 offset:47104
	ds_read_b128 v[196:199], v0 offset:49152
	ds_read_b128 v[200:203], v0 offset:51200
	ds_read_b128 v[204:207], v0 offset:53248
	ds_read_b128 v[208:211], v0 offset:55296
	s_cmpk_eq_i32 s10, 0x780
	s_cbranch_scc1 .Lmyg1267_loop
	s_and_b32 s16, s15, 0x10000
	s_add_i32 s16, s16, 0
	s_add_i32 s17, s16, 0x2000
	s_add_i32 s16, s16, 0xa000
	v_add_u32_e32 v224, s16, v136
	v_lshl_add_u64 v[222:223], v[160:161], 0, s[10:11]
	v_readfirstlane_b32 s18, v224
	v_add_u32_e32 v224, s17, v136
	s_mov_b32 m0, s18
	v_readfirstlane_b32 s18, v224
	v_add_u32_e32 v224, s16, v138
	global_load_lds_dwordx4 v[222:223], off
	v_lshl_add_u64 v[222:223], v[152:153], 0, s[10:11]
	s_mov_b32 m0, s18
	v_readfirstlane_b32 s18, v224
	v_add_u32_e32 v224, s17, v138
	global_load_lds_dwordx4 v[222:223], off
	v_lshl_add_u64 v[222:223], v[158:159], 0, s[10:11]
	s_mov_b32 m0, s18
	v_readfirstlane_b32 s18, v224
	v_add_u32_e32 v224, s16, v140
	global_load_lds_dwordx4 v[222:223], off
	v_lshl_add_u64 v[222:223], v[150:151], 0, s[10:11]
	s_mov_b32 m0, s18
	v_readfirstlane_b32 s18, v224
	v_add_u32_e32 v224, s17, v140
	global_load_lds_dwordx4 v[222:223], off
	v_lshl_add_u64 v[222:223], v[156:157], 0, s[10:11]
	s_mov_b32 m0, s18
	v_readfirstlane_b32 s18, v224
	v_add_u32_e32 v224, s16, v142
	global_load_lds_dwordx4 v[222:223], off
	v_lshl_add_u64 v[222:223], v[148:149], 0, s[10:11]
	s_mov_b32 m0, s18
	v_readfirstlane_b32 s16, v224
	v_add_u32_e32 v224, s17, v142
	global_load_lds_dwordx4 v[222:223], off
	v_lshl_add_u64 v[222:223], v[154:155], 0, s[10:11]
	s_mov_b32 m0, s16
	v_readfirstlane_b32 s16, v224
	global_load_lds_dwordx4 v[222:223], off
	v_lshl_add_u64 v[222:223], v[146:147], 0, s[10:11]
	s_mov_b32 m0, s16
	s_nop 0
	global_load_lds_dwordx4 v[222:223], off
.Lmyg1267_loop:
	s_waitcnt lgkmcnt(7)
	v_mfma_f32_16x16x32_bf16 v[126:129], v[130:133], v[180:183], v[126:129]
	ds_read_b128 v[226:229], v179 offset:10240
	s_waitcnt lgkmcnt(7)
	v_mfma_f32_16x16x32_bf16 v[118:121], v[130:133], v[184:187], v[118:121]
	s_waitcnt lgkmcnt(6)
	v_mfma_f32_16x16x32_bf16 v[110:113], v[130:133], v[188:191], v[110:113]
	s_waitcnt lgkmcnt(5)
	v_mfma_f32_16x16x32_bf16 v[102:105], v[130:133], v[192:195], v[102:105]
	s_waitcnt lgkmcnt(4)
	v_mfma_f32_16x16x32_bf16 v[94:97], v[130:133], v[196:199], v[94:97]
	s_waitcnt lgkmcnt(3)
	v_mfma_f32_16x16x32_bf16 v[86:89], v[130:133], v[200:203], v[86:89]
	s_waitcnt lgkmcnt(2)
	v_mfma_f32_16x16x32_bf16 v[78:81], v[130:133], v[204:207], v[78:81]
	s_waitcnt lgkmcnt(1)
	v_mfma_f32_16x16x32_bf16 v[70:73], v[130:133], v[208:211], v[70:73]
	s_waitcnt lgkmcnt(0)
	v_mfma_f32_16x16x32_bf16 v[122:125], v[226:229], v[180:183], v[122:125]
	ds_read_b128 v[130:133], v179 offset:12288
	v_mfma_f32_16x16x32_bf16 v[114:117], v[226:229], v[184:187], v[114:117]
	v_mfma_f32_16x16x32_bf16 v[106:109], v[226:229], v[188:191], v[106:109]
	v_mfma_f32_16x16x32_bf16 v[98:101], v[226:229], v[192:195], v[98:101]
	v_mfma_f32_16x16x32_bf16 v[90:93], v[226:229], v[196:199], v[90:93]
	v_mfma_f32_16x16x32_bf16 v[82:85], v[226:229], v[200:203], v[82:85]
	v_mfma_f32_16x16x32_bf16 v[74:77], v[226:229], v[204:207], v[74:77]
	v_mfma_f32_16x16x32_bf16 v[62:65], v[226:229], v[208:211], v[62:65]
	s_waitcnt lgkmcnt(0)
	v_mfma_f32_16x16x32_bf16 v[54:57], v[130:133], v[180:183], v[54:57]
	ds_read_b128 v[226:229], v179 offset:14336
	v_mfma_f32_16x16x32_bf16 v[46:49], v[130:133], v[184:187], v[46:49]
	v_add_u32_e32 v0, s100, v178
	v_mfma_f32_16x16x32_bf16 v[38:41], v[130:133], v[188:191], v[38:41]
	v_add3_u32 v179, v0, v175, v176
	v_mfma_f32_16x16x32_bf16 v[26:29], v[130:133], v[192:195], v[26:29]
	v_add3_u32 v0, v0, v177, v176
	v_mfma_f32_16x16x32_bf16 v[14:17], v[130:133], v[196:199], v[14:17]
	v_mfma_f32_16x16x32_bf16 v[10:13], v[130:133], v[200:203], v[10:13]
	v_mfma_f32_16x16x32_bf16 v[6:9], v[130:133], v[204:207], v[6:9]
	v_mfma_f32_16x16x32_bf16 v[2:5], v[130:133], v[208:211], v[2:5]
	s_waitcnt lgkmcnt(0)
	v_mfma_f32_16x16x32_bf16 v[66:69], v[226:229], v[180:183], v[66:69]
	ds_read_b128 v[130:133], v179 offset:8192
	ds_read_b128 v[180:183], v0 offset:40960
	v_mfma_f32_16x16x32_bf16 v[58:61], v[226:229], v[184:187], v[58:61]
	ds_read_b128 v[184:187], v0 offset:43008
	v_mfma_f32_16x16x32_bf16 v[50:53], v[226:229], v[188:191], v[50:53]
	ds_read_b128 v[188:191], v0 offset:45056
	v_mfma_f32_16x16x32_bf16 v[42:45], v[226:229], v[192:195], v[42:45]
	ds_read_b128 v[192:195], v0 offset:47104
	v_mfma_f32_16x16x32_bf16 v[30:33], v[226:229], v[196:199], v[30:33]
	ds_read_b128 v[196:199], v0 offset:49152
	v_mfma_f32_16x16x32_bf16 v[22:25], v[226:229], v[200:203], v[22:25]
	ds_read_b128 v[200:203], v0 offset:51200
	v_mfma_f32_16x16x32_bf16 v[18:21], v[226:229], v[204:207], v[18:21]
	ds_read_b128 v[204:207], v0 offset:53248
	v_mfma_f32_16x16x32_bf16 v[34:37], v[226:229], v[208:211], v[34:37]
	ds_read_b128 v[208:211], v0 offset:55296
	s_waitcnt lgkmcnt(7)
	v_mfma_f32_16x16x32_bf16 v[126:129], v[130:133], v[180:183], v[126:129]
	ds_read_b128 v[226:229], v179 offset:10240
	s_waitcnt lgkmcnt(7)
; #define MFMA16(a, b, c) __builtin_amdgcn_mfma_f32_16x16x32_bf16((a), (b), (c), 0, 0, 0)
; DI void vm_wait0() { asm volatile("s_waitcnt vmcnt(0)" ::: "memory"); }
;   DI unsigned koff(int k) const { return (unsigned)((k >> 6) * EIN + (k & 63)); }
; DI void dma16(const void* g, unsigned char* l) { __builtin_amdgcn_global_load_lds((const unsigned*)g, (lds_u32_t*)(unsigned)(size_t)l, 16, 0, 0); }
; template <class AF, class EF>
; DI void gemm_run(unsigned char* lds, int wv, const AF& af, const bf16_t* __restrict__ Bt, int ldb, int M, int N, int K, const EF& ef, int blk_off) {
;     ...
;     for (int kt = 0; kt < nk; ++kt) {
;       unsigned char* cur = sBase + (kt & 1) * GST;
;       if (kt + 1 < nk) {
;         unsigned char* nxt = sBase + ((kt + 1) & 1) * GST;
;         const int k0 = (kt + 1) << 6;
; #pragma unroll
;         for (int i = 0; i < 4; ++i) {
;           dma16(Ab + aoff[i] + af.koff(k0 + cch), nxt + 32768 + (i * 512 + tid) * 16);
;           dma16(Bt + boff[i] + (unsigned)k0, nxt + (i * 512 + tid) * 16);
;         }
;       }
; #pragma unroll
;       for (int ks = 0; ks < 2; ++ks) {
;         bf16x8 wf[4], xf[8];
; #pragma unroll
;         for (int i = 0; i < 4; ++i) wf[i] = *(const bf16x8*)(cur + (wn * 64 + i * 16 + l15) * 128 + (((ks * 4 + q4) ^ swz) * 16));
; #pragma unroll
;         for (int j = 0; j < 8; ++j) xf[j] = *(const bf16x8*)(cur + 32768 + (wm * 128 + j * 16 + l15) * 128 + (((ks * 4 + q4) ^ swz) * 16));
; #pragma unroll
;         for (int i = 0; i < 4; ++i)
; #pragma unroll
;           for (int j = 0; j < 8; ++j) acc[i][j] = MFMA16(wf[i], xf[j], acc[i][j]);
;       }
;       vm_wait0();
;       __syncthreads();
;     }
	v_mfma_f32_16x16x32_bf16 v[118:121], v[130:133], v[184:187], v[118:121]
	s_waitcnt lgkmcnt(6)
	v_mfma_f32_16x16x32_bf16 v[110:113], v[130:133], v[188:191], v[110:113]
	s_waitcnt lgkmcnt(5)
	v_mfma_f32_16x16x32_bf16 v[102:105], v[130:133], v[192:195], v[102:105]
	s_waitcnt lgkmcnt(4)
	v_mfma_f32_16x16x32_bf16 v[94:97], v[130:133], v[196:199], v[94:97]
	s_waitcnt lgkmcnt(3)
	v_mfma_f32_16x16x32_bf16 v[86:89], v[130:133], v[200:203], v[86:89]
	s_waitcnt lgkmcnt(2)
	v_mfma_f32_16x16x32_bf16 v[78:81], v[130:133], v[204:207], v[78:81]
	s_waitcnt lgkmcnt(1)
	v_mfma_f32_16x16x32_bf16 v[70:73], v[130:133], v[208:211], v[70:73]
	s_waitcnt lgkmcnt(0)
	v_mfma_f32_16x16x32_bf16 v[122:125], v[226:229], v[180:183], v[122:125]
	ds_read_b128 v[130:133], v179 offset:12288
	v_mfma_f32_16x16x32_bf16 v[114:117], v[226:229], v[184:187], v[114:117]
	v_mfma_f32_16x16x32_bf16 v[106:109], v[226:229], v[188:191], v[106:109]
	v_mfma_f32_16x16x32_bf16 v[98:101], v[226:229], v[192:195], v[98:101]
	v_mfma_f32_16x16x32_bf16 v[90:93], v[226:229], v[196:199], v[90:93]
	v_mfma_f32_16x16x32_bf16 v[82:85], v[226:229], v[200:203], v[82:85]
	v_mfma_f32_16x16x32_bf16 v[74:77], v[226:229], v[204:207], v[74:77]
	v_mfma_f32_16x16x32_bf16 v[62:65], v[226:229], v[208:211], v[62:65]
	s_waitcnt lgkmcnt(0)
	v_mfma_f32_16x16x32_bf16 v[54:57], v[130:133], v[180:183], v[54:57]
	ds_read_b128 v[226:229], v179 offset:14336
	v_mfma_f32_16x16x32_bf16 v[46:49], v[130:133], v[184:187], v[46:49]
	v_mfma_f32_16x16x32_bf16 v[38:41], v[130:133], v[188:191], v[38:41]
	v_mfma_f32_16x16x32_bf16 v[26:29], v[130:133], v[192:195], v[26:29]
	v_mfma_f32_16x16x32_bf16 v[14:17], v[130:133], v[196:199], v[14:17]
	v_mfma_f32_16x16x32_bf16 v[10:13], v[130:133], v[200:203], v[10:13]
	v_mfma_f32_16x16x32_bf16 v[6:9], v[130:133], v[204:207], v[6:9]
	v_mfma_f32_16x16x32_bf16 v[2:5], v[130:133], v[208:211], v[2:5]
	s_waitcnt vmcnt(0) lgkmcnt(0)
	s_barrier
	s_add_u32 s10, s10, 0x80
	s_addc_u32 s11, s11, 0
	s_add_i32 s15, s15, 0x10000
	s_cmpk_eq_i32 s10, 0x800
	s_cbranch_scc1 .Lmyg1267_tail
	s_add_i32 s100, s15, 0xffff0000
	s_and_b32 s100, s100, 0x10000
	v_add_u32_e32 v0, s100, v174
	v_add3_u32 v179, v0, v175, v176
	v_add3_u32 v0, v0, v177, v176
	s_cmpk_eq_i32 s10, 0x780
	v_mfma_f32_16x16x32_bf16 v[66:69], v[226:229], v[180:183], v[66:69]
	ds_read_b128 v[130:133], v179 offset:8192
	ds_read_b128 v[180:183], v0 offset:40960
	v_mfma_f32_16x16x32_bf16 v[58:61], v[226:229], v[184:187], v[58:61]
	ds_read_b128 v[184:187], v0 offset:43008
	v_mfma_f32_16x16x32_bf16 v[50:53], v[226:229], v[188:191], v[50:53]
	ds_read_b128 v[188:191], v0 offset:45056
	v_mfma_f32_16x16x32_bf16 v[42:45], v[226:229], v[192:195], v[42:45]
	ds_read_b128 v[192:195], v0 offset:47104
	v_mfma_f32_16x16x32_bf16 v[30:33], v[226:229], v[196:199], v[30:33]
	ds_read_b128 v[196:199], v0 offset:49152
	v_mfma_f32_16x16x32_bf16 v[22:25], v[226:229], v[200:203], v[22:25]
	ds_read_b128 v[200:203], v0 offset:51200
	v_mfma_f32_16x16x32_bf16 v[18:21], v[226:229], v[204:207], v[18:21]
	ds_read_b128 v[204:207], v0 offset:53248
	v_mfma_f32_16x16x32_bf16 v[34:37], v[226:229], v[208:211], v[34:37]
	ds_read_b128 v[208:211], v0 offset:55296
	s_cbranch_scc1 .Lmyg1267_loop
	s_and_b32 s16, s15, 0x10000
	s_add_i32 s16, s16, 0
	s_add_i32 s17, s16, 0x2000
	s_add_i32 s16, s16, 0xa000
	v_add_u32_e32 v224, s16, v136
	v_lshl_add_u64 v[222:223], v[160:161], 0, s[10:11]
	v_readfirstlane_b32 s18, v224
	v_add_u32_e32 v224, s17, v136
	s_mov_b32 m0, s18
	v_readfirstlane_b32 s18, v224
	v_add_u32_e32 v224, s16, v138
	global_load_lds_dwordx4 v[222:223], off
	v_lshl_add_u64 v[222:223], v[152:153], 0, s[10:11]
	s_mov_b32 m0, s18
	v_readfirstlane_b32 s18, v224
	v_add_u32_e32 v224, s17, v138
	global_load_lds_dwordx4 v[222:223], off
	v_lshl_add_u64 v[222:223], v[158:159], 0, s[10:11]
	s_mov_b32 m0, s18
	v_readfirstlane_b32 s18, v224
	v_add_u32_e32 v224, s16, v140
	global_load_lds_dwordx4 v[222:223], off
	v_lshl_add_u64 v[222:223], v[150:151], 0, s[10:11]
	s_mov_b32 m0, s18
	v_readfirstlane_b32 s18, v224
	v_add_u32_e32 v224, s17, v140
	global_load_lds_dwordx4 v[222:223], off
	v_lshl_add_u64 v[222:223], v[156:157], 0, s[10:11]
	s_mov_b32 m0, s18
	v_readfirstlane_b32 s18, v224
	v_add_u32_e32 v224, s16, v142
	global_load_lds_dwordx4 v[222:223], off
	v_lshl_add_u64 v[222:223], v[148:149], 0, s[10:11]
	s_mov_b32 m0, s18
	v_readfirstlane_b32 s16, v224
	v_add_u32_e32 v224, s17, v142
	global_load_lds_dwordx4 v[222:223], off
	v_lshl_add_u64 v[222:223], v[154:155], 0, s[10:11]
	s_mov_b32 m0, s16
	v_readfirstlane_b32 s16, v224
	global_load_lds_dwordx4 v[222:223], off
	v_lshl_add_u64 v[222:223], v[146:147], 0, s[10:11]
	s_mov_b32 m0, s16
	s_nop 0
	global_load_lds_dwordx4 v[222:223], off
	s_branch .Lmyg1267_loop
.Lmyg1267_tail:
	v_mfma_f32_16x16x32_bf16 v[66:69], v[226:229], v[180:183], v[66:69]
	v_mfma_f32_16x16x32_bf16 v[58:61], v[226:229], v[184:187], v[58:61]
	v_mfma_f32_16x16x32_bf16 v[50:53], v[226:229], v[188:191], v[50:53]
	v_mfma_f32_16x16x32_bf16 v[42:45], v[226:229], v[192:195], v[42:45]
	v_mfma_f32_16x16x32_bf16 v[30:33], v[226:229], v[196:199], v[30:33]
	v_mfma_f32_16x16x32_bf16 v[22:25], v[226:229], v[200:203], v[22:25]
	v_mfma_f32_16x16x32_bf16 v[18:21], v[226:229], v[204:207], v[18:21]
	v_mfma_f32_16x16x32_bf16 v[34:37], v[226:229], v[208:211], v[34:37]
	s_branch .LBB0_1265

; #define MFMA16(a, b, c) __builtin_amdgcn_mfma_f32_16x16x32_bf16((a), (b), (c), 0, 0, 0)
; DI void vm_wait0() { asm volatile("s_waitcnt vmcnt(0)" ::: "memory"); }
;   DI unsigned koff(int k) const { return (unsigned)((k >> 6) * EIN + (k & 63)); }
; DI void dma16(const void* g, unsigned char* l) { __builtin_amdgcn_global_load_lds((const unsigned*)g, (lds_u32_t*)(unsigned)(size_t)l, 16, 0, 0); }
; template <class AF, class EF>
; DI void gemm_run(unsigned char* lds, int wv, const AF& af, const bf16_t* __restrict__ Bt, int ldb, int M, int N, int K, const EF& ef, int blk_off) {
;     ...
;     for (int kt = 0; kt < nk; ++kt) {
;       unsigned char* cur = sBase + (kt & 1) * GST;
;       if (kt + 1 < nk) {
;         unsigned char* nxt = sBase + ((kt + 1) & 1) * GST;
;         const int k0 = (kt + 1) << 6;
; #pragma unroll
;         for (int i = 0; i < 4; ++i) {
;           dma16(Ab + aoff[i] + af.koff(k0 + cch), nxt + 32768 + (i * 512 + tid) * 16);
;           dma16(Bt + boff[i] + (unsigned)k0, nxt + (i * 512 + tid) * 16);
;         }
;       }
; #pragma unroll
;       for (int ks = 0; ks < 2; ++ks) {
;         bf16x8 wf[4], xf[8];
; #pragma unroll
;         for (int i = 0; i < 4; ++i) wf[i] = *(const bf16x8*)(cur + (wn * 64 + i * 16 + l15) * 128 + (((ks * 4 + q4) ^ swz) * 16));
; #pragma unroll
;         for (int j = 0; j < 8; ++j) xf[j] = *(const bf16x8*)(cur + 32768 + (wm * 128 + j * 16 + l15) * 128 + (((ks * 4 + q4) ^ swz) * 16));
; #pragma unroll
;         for (int i = 0; i < 4; ++i)
; #pragma unroll
;           for (int j = 0; j < 8; ++j) acc[i][j] = MFMA16(wf[i], xf[j], acc[i][j]);
;       }
;       vm_wait0();
;       __syncthreads();
;     }
.LBB0_1280:
	s_add_i32 s100, s22, 0xffff0000
	s_and_b32 s100, s100, 0x10000
	v_add_u32_e32 v0, s100, v179
	v_add3_u32 v212, v0, v180, v181
	v_add3_u32 v0, v0, v182, v181
	ds_read_b128 v[130:133], v212 offset:8192
	ds_read_b128 v[184:187], v0 offset:43008
	ds_read_b128 v[134:137], v0 offset:40960
	ds_read_b128 v[188:191], v0 offset:45056
	ds_read_b128 v[192:195], v0 offset:47104
	ds_read_b128 v[196:199], v0 offset:49152
	ds_read_b128 v[200:203], v0 offset:51200
	ds_read_b128 v[204:207], v0 offset:53248
	ds_read_b128 v[208:211], v0 offset:55296
	s_cmp_gt_u32 s21, 62
	s_cbranch_scc1 .Lmyg1279_loop
	s_and_b32 s23, s22, 0x10000
	s_add_i32 s23, s23, 0
	s_add_i32 s24, s23, 0x2000
	s_add_i32 s23, s23, 0xa000
	v_add_u32_e32 v224, s23, v140
	v_lshl_add_u64 v[222:223], v[166:167], 0, s[16:17]
	v_readfirstlane_b32 s25, v224
	v_add_u32_e32 v224, s24, v140
	s_mov_b32 m0, s25
	v_readfirstlane_b32 s25, v224
	v_add_u32_e32 v224, s23, v142
	global_load_lds_dwordx4 v[222:223], off
	v_lshl_add_u64 v[222:223], v[156:157], 0, s[16:17]
	s_mov_b32 m0, s25
	v_readfirstlane_b32 s25, v224
	v_add_u32_e32 v224, s24, v142
	global_load_lds_dwordx4 v[222:223], off
	v_lshl_add_u64 v[222:223], v[164:165], 0, s[16:17]
	s_mov_b32 m0, s25
	v_readfirstlane_b32 s25, v224
	v_add_u32_e32 v224, s23, v144
	global_load_lds_dwordx4 v[222:223], off
	v_lshl_add_u64 v[222:223], v[154:155], 0, s[16:17]
	s_mov_b32 m0, s25
	v_readfirstlane_b32 s25, v224
	v_add_u32_e32 v224, s24, v144
	global_load_lds_dwordx4 v[222:223], off
	v_lshl_add_u64 v[222:223], v[160:161], 0, s[16:17]
	s_mov_b32 m0, s25
	v_readfirstlane_b32 s25, v224
	v_add_u32_e32 v224, s23, v146
	global_load_lds_dwordx4 v[222:223], off
	v_lshl_add_u64 v[222:223], v[152:153], 0, s[16:17]
	s_mov_b32 m0, s25
	v_readfirstlane_b32 s23, v224
	v_add_u32_e32 v224, s24, v146
	global_load_lds_dwordx4 v[222:223], off
	v_lshl_add_u64 v[222:223], v[158:159], 0, s[16:17]
	s_mov_b32 m0, s23
	v_readfirstlane_b32 s23, v224
	global_load_lds_dwordx4 v[222:223], off
	v_lshl_add_u64 v[222:223], v[150:151], 0, s[16:17]
	s_mov_b32 m0, s23
	s_nop 0
	global_load_lds_dwordx4 v[222:223], off
.Lmyg1279_loop:
	s_waitcnt lgkmcnt(7)
	v_mfma_f32_16x16x32_bf16 v[118:121], v[130:133], v[184:187], v[118:121]
	ds_read_b128 v[226:229], v212 offset:10240
	s_waitcnt lgkmcnt(7)
	v_mfma_f32_16x16x32_bf16 v[126:129], v[130:133], v[134:137], v[126:129]
	s_waitcnt lgkmcnt(6)
	v_mfma_f32_16x16x32_bf16 v[110:113], v[130:133], v[188:191], v[110:113]
	s_waitcnt lgkmcnt(5)
	v_mfma_f32_16x16x32_bf16 v[102:105], v[130:133], v[192:195], v[102:105]
	s_waitcnt lgkmcnt(4)
	v_mfma_f32_16x16x32_bf16 v[94:97], v[130:133], v[196:199], v[94:97]
	s_waitcnt lgkmcnt(3)
	v_mfma_f32_16x16x32_bf16 v[86:89], v[130:133], v[200:203], v[86:89]
	s_waitcnt lgkmcnt(2)
	v_mfma_f32_16x16x32_bf16 v[78:81], v[130:133], v[204:207], v[78:81]
	s_waitcnt lgkmcnt(1)
	v_mfma_f32_16x16x32_bf16 v[70:73], v[130:133], v[208:211], v[70:73]
	s_waitcnt lgkmcnt(0)
	v_mfma_f32_16x16x32_bf16 v[122:125], v[226:229], v[134:137], v[122:125]
	ds_read_b128 v[130:133], v212 offset:12288
	v_mfma_f32_16x16x32_bf16 v[114:117], v[226:229], v[184:187], v[114:117]
	v_mfma_f32_16x16x32_bf16 v[106:109], v[226:229], v[188:191], v[106:109]
	v_mfma_f32_16x16x32_bf16 v[98:101], v[226:229], v[192:195], v[98:101]
	v_mfma_f32_16x16x32_bf16 v[90:93], v[226:229], v[196:199], v[90:93]
	v_mfma_f32_16x16x32_bf16 v[82:85], v[226:229], v[200:203], v[82:85]
	v_mfma_f32_16x16x32_bf16 v[74:77], v[226:229], v[204:207], v[74:77]
	v_mfma_f32_16x16x32_bf16 v[66:69], v[226:229], v[208:211], v[66:69]
	s_waitcnt lgkmcnt(0)
	v_mfma_f32_16x16x32_bf16 v[58:61], v[130:133], v[134:137], v[58:61]
	ds_read_b128 v[226:229], v212 offset:14336
	v_mfma_f32_16x16x32_bf16 v[50:53], v[130:133], v[184:187], v[50:53]
	v_add_u32_e32 v0, s100, v183
	v_mfma_f32_16x16x32_bf16 v[42:45], v[130:133], v[188:191], v[42:45]
	v_add3_u32 v212, v0, v180, v181
	v_mfma_f32_16x16x32_bf16 v[30:33], v[130:133], v[192:195], v[30:33]
	v_add3_u32 v0, v0, v182, v181
	v_mfma_f32_16x16x32_bf16 v[14:17], v[130:133], v[196:199], v[14:17]
	v_mfma_f32_16x16x32_bf16 v[10:13], v[130:133], v[200:203], v[10:13]
	v_mfma_f32_16x16x32_bf16 v[6:9], v[130:133], v[204:207], v[6:9]
	v_mfma_f32_16x16x32_bf16 v[2:5], v[130:133], v[208:211], v[2:5]
	s_waitcnt lgkmcnt(0)
	v_mfma_f32_16x16x32_bf16 v[54:57], v[226:229], v[184:187], v[54:57]
	ds_read_b128 v[130:133], v212 offset:8192
	ds_read_b128 v[184:187], v0 offset:43008
	v_mfma_f32_16x16x32_bf16 v[62:65], v[226:229], v[134:137], v[62:65]
	ds_read_b128 v[134:137], v0 offset:40960
	v_mfma_f32_16x16x32_bf16 v[46:49], v[226:229], v[188:191], v[46:49]
	ds_read_b128 v[188:191], v0 offset:45056
	v_mfma_f32_16x16x32_bf16 v[38:41], v[226:229], v[192:195], v[38:41]
	ds_read_b128 v[192:195], v0 offset:47104
	v_mfma_f32_16x16x32_bf16 v[26:29], v[226:229], v[196:199], v[26:29]
	ds_read_b128 v[196:199], v0 offset:49152
	v_mfma_f32_16x16x32_bf16 v[22:25], v[226:229], v[200:203], v[22:25]
	ds_read_b128 v[200:203], v0 offset:51200
	v_mfma_f32_16x16x32_bf16 v[34:37], v[226:229], v[204:207], v[34:37]
	ds_read_b128 v[204:207], v0 offset:53248
	v_mfma_f32_16x16x32_bf16 v[18:21], v[226:229], v[208:211], v[18:21]
	ds_read_b128 v[208:211], v0 offset:55296
	s_waitcnt lgkmcnt(7)
; #define MFMA16(a, b, c) __builtin_amdgcn_mfma_f32_16x16x32_bf16((a), (b), (c), 0, 0, 0)
; DI void vm_wait0() { asm volatile("s_waitcnt vmcnt(0)" ::: "memory"); }
;   DI unsigned koff(int k) const { return (unsigned)((k >> 6) * EIN + (k & 63)); }
; DI void dma16(const void* g, unsigned char* l) { __builtin_amdgcn_global_load_lds((const unsigned*)g, (lds_u32_t*)(unsigned)(size_t)l, 16, 0, 0); }
; template <class AF, class EF>
; DI void gemm_run(unsigned char* lds, int wv, const AF& af, const bf16_t* __restrict__ Bt, int ldb, int M, int N, int K, const EF& ef, int blk_off) {
;     ...
;     for (int kt = 0; kt < nk; ++kt) {
;       unsigned char* cur = sBase + (kt & 1) * GST;
;       if (kt + 1 < nk) {
;         unsigned char* nxt = sBase + ((kt + 1) & 1) * GST;
;         const int k0 = (kt + 1) << 6;
; #pragma unroll
;         for (int i = 0; i < 4; ++i) {
;           dma16(Ab + aoff[i] + af.koff(k0 + cch), nxt + 32768 + (i * 512 + tid) * 16);
;           dma16(Bt + boff[i] + (unsigned)k0, nxt + (i * 512 + tid) * 16);
;         }
;       }
; #pragma unroll
;       for (int ks = 0; ks < 2; ++ks) {
;         bf16x8 wf[4], xf[8];
; #pragma unroll
;         for (int i = 0; i < 4; ++i) wf[i] = *(const bf16x8*)(cur + (wn * 64 + i * 16 + l15) * 128 + (((ks * 4 + q4) ^ swz) * 16));
; #pragma unroll
;         for (int j = 0; j < 8; ++j) xf[j] = *(const bf16x8*)(cur + 32768 + (wm * 128 + j * 16 + l15) * 128 + (((ks * 4 + q4) ^ swz) * 16));
; #pragma unroll
;         for (int i = 0; i < 4; ++i)
; #pragma unroll
;           for (int j = 0; j < 8; ++j) acc[i][j] = MFMA16(wf[i], xf[j], acc[i][j]);
;       }
;       vm_wait0();
;       __syncthreads();
;     }
	v_mfma_f32_16x16x32_bf16 v[118:121], v[130:133], v[184:187], v[118:121]
	ds_read_b128 v[226:229], v212 offset:10240
	s_waitcnt lgkmcnt(7)
	v_mfma_f32_16x16x32_bf16 v[126:129], v[130:133], v[134:137], v[126:129]
	s_waitcnt lgkmcnt(6)
	v_mfma_f32_16x16x32_bf16 v[110:113], v[130:133], v[188:191], v[110:113]
	s_waitcnt lgkmcnt(5)
	v_mfma_f32_16x16x32_bf16 v[102:105], v[130:133], v[192:195], v[102:105]
	s_waitcnt lgkmcnt(4)
	v_mfma_f32_16x16x32_bf16 v[94:97], v[130:133], v[196:199], v[94:97]
	s_waitcnt lgkmcnt(3)
	v_mfma_f32_16x16x32_bf16 v[86:89], v[130:133], v[200:203], v[86:89]
	s_waitcnt lgkmcnt(2)
	v_mfma_f32_16x16x32_bf16 v[78:81], v[130:133], v[204:207], v[78:81]
	s_waitcnt lgkmcnt(1)
	v_mfma_f32_16x16x32_bf16 v[70:73], v[130:133], v[208:211], v[70:73]
	s_waitcnt lgkmcnt(0)
	v_mfma_f32_16x16x32_bf16 v[122:125], v[226:229], v[134:137], v[122:125]
	ds_read_b128 v[130:133], v212 offset:12288
	v_mfma_f32_16x16x32_bf16 v[114:117], v[226:229], v[184:187], v[114:117]
	v_mfma_f32_16x16x32_bf16 v[106:109], v[226:229], v[188:191], v[106:109]
	v_mfma_f32_16x16x32_bf16 v[98:101], v[226:229], v[192:195], v[98:101]
	v_mfma_f32_16x16x32_bf16 v[90:93], v[226:229], v[196:199], v[90:93]
	v_mfma_f32_16x16x32_bf16 v[82:85], v[226:229], v[200:203], v[82:85]
	v_mfma_f32_16x16x32_bf16 v[74:77], v[226:229], v[204:207], v[74:77]
	v_mfma_f32_16x16x32_bf16 v[66:69], v[226:229], v[208:211], v[66:69]
	s_waitcnt lgkmcnt(0)
	v_mfma_f32_16x16x32_bf16 v[58:61], v[130:133], v[134:137], v[58:61]
	ds_read_b128 v[226:229], v212 offset:14336
	v_mfma_f32_16x16x32_bf16 v[50:53], v[130:133], v[184:187], v[50:53]
	v_mfma_f32_16x16x32_bf16 v[42:45], v[130:133], v[188:191], v[42:45]
	v_mfma_f32_16x16x32_bf16 v[30:33], v[130:133], v[192:195], v[30:33]
	v_mfma_f32_16x16x32_bf16 v[14:17], v[130:133], v[196:199], v[14:17]
	v_mfma_f32_16x16x32_bf16 v[10:13], v[130:133], v[200:203], v[10:13]
	v_mfma_f32_16x16x32_bf16 v[6:9], v[130:133], v[204:207], v[6:9]
	v_mfma_f32_16x16x32_bf16 v[2:5], v[130:133], v[208:211], v[2:5]
	s_waitcnt vmcnt(0) lgkmcnt(0)
	s_barrier
	s_add_u32 s16, s16, 0x80
	s_addc_u32 s17, s17, 0
	s_add_i32 s22, s22, 0x10000
	s_add_i32 s21, s21, 1
	s_cmpk_eq_i32 s16, 0x2000
	s_cbranch_scc1 .Lmyg1279_tail
	s_add_i32 s100, s22, 0xffff0000
	s_and_b32 s100, s100, 0x10000
	v_add_u32_e32 v0, s100, v179
	v_add3_u32 v212, v0, v180, v181
	v_add3_u32 v0, v0, v182, v181
	s_cmp_gt_u32 s21, 62
	v_mfma_f32_16x16x32_bf16 v[54:57], v[226:229], v[184:187], v[54:57]
	ds_read_b128 v[130:133], v212 offset:8192
	ds_read_b128 v[184:187], v0 offset:43008
	v_mfma_f32_16x16x32_bf16 v[62:65], v[226:229], v[134:137], v[62:65]
	ds_read_b128 v[134:137], v0 offset:40960
	v_mfma_f32_16x16x32_bf16 v[46:49], v[226:229], v[188:191], v[46:49]
	ds_read_b128 v[188:191], v0 offset:45056
	v_mfma_f32_16x16x32_bf16 v[38:41], v[226:229], v[192:195], v[38:41]
	ds_read_b128 v[192:195], v0 offset:47104
	v_mfma_f32_16x16x32_bf16 v[26:29], v[226:229], v[196:199], v[26:29]
	ds_read_b128 v[196:199], v0 offset:49152
	v_mfma_f32_16x16x32_bf16 v[22:25], v[226:229], v[200:203], v[22:25]
	ds_read_b128 v[200:203], v0 offset:51200
	v_mfma_f32_16x16x32_bf16 v[34:37], v[226:229], v[204:207], v[34:37]
	ds_read_b128 v[204:207], v0 offset:53248
	v_mfma_f32_16x16x32_bf16 v[18:21], v[226:229], v[208:211], v[18:21]
	ds_read_b128 v[208:211], v0 offset:55296
	s_cbranch_scc1 .Lmyg1279_loop
	s_and_b32 s23, s22, 0x10000
	s_add_i32 s23, s23, 0
	s_add_i32 s24, s23, 0x2000
	s_add_i32 s23, s23, 0xa000
	v_add_u32_e32 v224, s23, v140
	v_lshl_add_u64 v[222:223], v[166:167], 0, s[16:17]
	v_readfirstlane_b32 s25, v224
	v_add_u32_e32 v224, s24, v140
	s_mov_b32 m0, s25
	v_readfirstlane_b32 s25, v224
	v_add_u32_e32 v224, s23, v142
	global_load_lds_dwordx4 v[222:223], off
	v_lshl_add_u64 v[222:223], v[156:157], 0, s[16:17]
	s_mov_b32 m0, s25
	v_readfirstlane_b32 s25, v224
	v_add_u32_e32 v224, s24, v142
	global_load_lds_dwordx4 v[222:223], off
	v_lshl_add_u64 v[222:223], v[164:165], 0, s[16:17]
	s_mov_b32 m0, s25
	v_readfirstlane_b32 s25, v224
	v_add_u32_e32 v224, s23, v144
	global_load_lds_dwordx4 v[222:223], off
	v_lshl_add_u64 v[222:223], v[154:155], 0, s[16:17]
	s_mov_b32 m0, s25
	v_readfirstlane_b32 s25, v224
	v_add_u32_e32 v224, s24, v144
	global_load_lds_dwordx4 v[222:223], off
	v_lshl_add_u64 v[222:223], v[160:161], 0, s[16:17]
	s_mov_b32 m0, s25
	v_readfirstlane_b32 s25, v224
	v_add_u32_e32 v224, s23, v146
	global_load_lds_dwordx4 v[222:223], off
	v_lshl_add_u64 v[222:223], v[152:153], 0, s[16:17]
	s_mov_b32 m0, s25
	v_readfirstlane_b32 s23, v224
	v_add_u32_e32 v224, s24, v146
	global_load_lds_dwordx4 v[222:223], off
	v_lshl_add_u64 v[222:223], v[158:159], 0, s[16:17]
	s_mov_b32 m0, s23
	v_readfirstlane_b32 s23, v224
	global_load_lds_dwordx4 v[222:223], off
	v_lshl_add_u64 v[222:223], v[150:151], 0, s[16:17]
	s_mov_b32 m0, s23
	s_nop 0
	global_load_lds_dwordx4 v[222:223], off
	s_branch .Lmyg1279_loop

; __global__ void __launch_bounds__(NTHREADS) mega(Params P0) {
;   extern __shared__ __attribute__((aligned(16))) unsigned char lds[];
	.amdhsa_kernel _Z4mega6Params
		.amdhsa_group_segment_fixed_size 0
		.amdhsa_private_segment_fixed_size 0
		.amdhsa_kernarg_size 472
		.amdhsa_user_sgpr_count 2
		.amdhsa_user_sgpr_dispatch_ptr 0
		.amdhsa_user_sgpr_queue_ptr 0
		.amdhsa_user_sgpr_kernarg_segment_ptr 1
		.amdhsa_user_sgpr_dispatch_id 0
		.amdhsa_user_sgpr_kernarg_preload_length 0
		.amdhsa_user_sgpr_kernarg_preload_offset 0
		.amdhsa_user_sgpr_private_segment_size 0
		.amdhsa_uses_dynamic_stack 0
		.amdhsa_enable_private_segment 0
		.amdhsa_system_sgpr_workgroup_id_x 1
		.amdhsa_system_sgpr_workgroup_id_y 0
		.amdhsa_system_sgpr_workgroup_id_z 0
		.amdhsa_system_sgpr_workgroup_info 0
		.amdhsa_system_vgpr_workitem_id 2
		.amdhsa_next_free_vgpr 256
		.amdhsa_next_free_sgpr 102
		.amdhsa_accum_offset 256
		.amdhsa_reserve_vcc 1
		.amdhsa_float_round_mode_32 0
		.amdhsa_float_round_mode_16_64 0
		.amdhsa_float_denorm_mode_32 3
		.amdhsa_float_denorm_mode_16_64 3
		.amdhsa_dx10_clamp 1
		.amdhsa_ieee_mode 1
		.amdhsa_fp16_overflow 0
		.amdhsa_tg_split 0
		.amdhsa_exception_fp_ieee_invalid_op 0
		.amdhsa_exception_fp_denorm_src 0
		.amdhsa_exception_fp_ieee_div_zero 0
		.amdhsa_exception_fp_ieee_overflow 0
		.amdhsa_exception_fp_ieee_underflow 0
		.amdhsa_exception_fp_ieee_inexact 0
		.amdhsa_exception_int_div_zero 0
	.end_amdhsa_kernel

; __global__ void __launch_bounds__(NTHREADS) mega(Params P0) {
;   extern __shared__ __attribute__((aligned(16))) unsigned char lds[];
amdhsa.kernels:
  - .agpr_count:     0
    .args:
      - .offset:         0
        .size:           216
        .value_kind:     by_value
      - .offset:         216
        .size:           4
        .value_kind:     hidden_block_count_x
      - .offset:         220
        .size:           4
        .value_kind:     hidden_block_count_y
      - .offset:         224
        .size:           4
        .value_kind:     hidden_block_count_z
      - .offset:         228
        .size:           2
        .value_kind:     hidden_group_size_x
      - .offset:         230
        .size:           2
        .value_kind:     hidden_group_size_y
      - .offset:         232
        .size:           2
        .value_kind:     hidden_group_size_z
      - .offset:         234
        .size:           2
        .value_kind:     hidden_remainder_x
      - .offset:         236
        .size:           2
        .value_kind:     hidden_remainder_y
      - .offset:         238
        .size:           2
        .value_kind:     hidden_remainder_z
      - .offset:         256
        .size:           8
        .value_kind:     hidden_global_offset_x
      - .offset:         264
        .size:           8
        .value_kind:     hidden_global_offset_y
      - .offset:         272
        .size:           8
        .value_kind:     hidden_global_offset_z
      - .offset:         280
        .size:           2
        .value_kind:     hidden_grid_dims
      - .offset:         304
        .size:           8
        .value_kind:     hidden_multigrid_sync_arg
      - .offset:         336
        .size:           4
        .value_kind:     hidden_dynamic_lds_size
    .group_segment_fixed_size: 0
    .kernarg_segment_align: 8
    .kernarg_segment_size: 472
    .language:       OpenCL C
    .language_version:
      - 2
      - 0
    .max_flat_workgroup_size: 512
    .name:           _Z4mega6Params
    .private_segment_fixed_size: 0
    .sgpr_count:     108
    .sgpr_spill_count: 97
    .symbol:         _Z4mega6Params.kd
    .uniform_work_group_size: 1
    .uses_dynamic_stack: false
    .vgpr_count:     256
    .vgpr_spill_count: 0
    .wavefront_size: 64
